# row-norm seams: 64-lane butterfly sums via DPP moves and permlane16/32 swaps instead of 6 ds_bpermute LDS round trips per reduction (bit-identical)
# speedup vs baseline: 1.0147x; 1.0081x over previous
.LBB0_73:
	s_or_b64 exec, exec, s[0:1]
	s_waitcnt vmcnt(11)
	v_mov_b32_e32 v132, v97
	v_mov_b32_e32 v133, v101
	v_mov_b32_e32 v130, v96
	v_mov_b32_e32 v131, v100
	v_pk_mul_f32 v[132:133], v[132:133], v[132:133]
	v_pk_mul_f32 v[126:127], v[48:49], v[48:49]
	v_pk_fma_f32 v[130:131], v[130:131], v[130:131], v[132:133]
	v_mov_b32_e32 v132, v98
	v_mov_b32_e32 v133, v102
	v_pk_fma_f32 v[130:131], v[132:133], v[132:133], v[130:131]
	v_mov_b32_e32 v132, v99
	v_mov_b32_e32 v133, v103
	v_pk_fma_f32 v[130:131], v[132:133], v[132:133], v[130:131]
	s_waitcnt vmcnt(10)
	v_mov_b32_e32 v132, v84
	v_mov_b32_e32 v133, v80
	v_pk_fma_f32 v[130:131], v[132:133], v[132:133], v[130:131]
	v_mov_b32_e32 v132, v85
	v_mov_b32_e32 v133, v81
	v_pk_fma_f32 v[130:131], v[132:133], v[132:133], v[130:131]
	v_mov_b32_e32 v132, v86
	v_mov_b32_e32 v133, v82
	v_pk_fma_f32 v[130:131], v[132:133], v[132:133], v[130:131]
	v_mov_b32_e32 v132, v87
	v_mov_b32_e32 v133, v83
	v_pk_fma_f32 v[130:131], v[132:133], v[132:133], v[130:131]
	s_waitcnt vmcnt(9)
	v_mov_b32_e32 v132, v68
	v_mov_b32_e32 v133, v64
	v_pk_fma_f32 v[130:131], v[132:133], v[132:133], v[130:131]
	v_mov_b32_e32 v132, v69
	v_mov_b32_e32 v133, v65
	v_pk_fma_f32 v[130:131], v[132:133], v[132:133], v[130:131]
	v_mov_b32_e32 v132, v70
	v_mov_b32_e32 v133, v66
	s_waitcnt vmcnt(8)
	v_pk_mul_f32 v[136:137], v[52:53], v[52:53]
	v_pk_fma_f32 v[130:131], v[132:133], v[132:133], v[130:131]
	v_mov_b32_e32 v132, v71
	v_mov_b32_e32 v133, v67
	v_pk_fma_f32 v[130:131], v[132:133], v[132:133], v[130:131]
	v_mov_b32_e32 v132, v136
	v_mov_b32_e32 v133, v126
	v_pk_mul_f32 v[124:125], v[50:51], v[50:51]
	v_pk_mul_f32 v[134:135], v[54:55], v[54:55]
	v_pk_add_f32 v[130:131], v[132:133], v[130:131]
	v_mov_b32_e32 v126, v137
	s_waitcnt vmcnt(3)
	v_mov_b32_e32 v136, v109
	v_mov_b32_e32 v137, v105
	v_pk_add_f32 v[126:127], v[126:127], v[130:131]
	v_mov_b32_e32 v130, v134
	v_mov_b32_e32 v131, v124
	v_mov_b32_e32 v124, v135
	v_mov_b32_e32 v134, v108
	v_mov_b32_e32 v135, v104
	v_pk_mul_f32 v[136:137], v[136:137], v[136:137]
	v_pk_add_f32 v[126:127], v[130:131], v[126:127]
	v_pk_fma_f32 v[134:135], v[134:135], v[134:135], v[136:137]
	v_mov_b32_e32 v136, v110
	v_mov_b32_e32 v137, v106
	v_pk_fma_f32 v[134:135], v[136:137], v[136:137], v[134:135]
	v_mov_b32_e32 v136, v111
	v_mov_b32_e32 v137, v107
	v_pk_add_f32 v[124:125], v[124:125], v[126:127]
	v_pk_fma_f32 v[134:135], v[136:137], v[136:137], v[134:135]
	s_waitcnt vmcnt(2)
	v_mov_b32_e32 v136, v92
	v_mov_b32_e32 v137, v88
	v_mov_b32_e32 v127, v125
	v_mov_b32_e32 v126, v124
	s_nop 1
	v_permlane32_swap_b32 v125, v127
	v_permlane32_swap_b32 v124, v126
	v_pk_fma_f32 v[134:135], v[136:137], v[136:137], v[134:135]
	v_mov_b32_e32 v136, v93
	v_mov_b32_e32 v137, v89
	v_pk_fma_f32 v[134:135], v[136:137], v[136:137], v[134:135]
	v_mov_b32_e32 v136, v94
	v_mov_b32_e32 v137, v90
	v_pk_fma_f32 v[134:135], v[136:137], v[136:137], v[134:135]
	v_mov_b32_e32 v136, v95
	v_mov_b32_e32 v137, v91
	v_pk_fma_f32 v[134:135], v[136:137], v[136:137], v[134:135]
	s_waitcnt vmcnt(1)
	v_mov_b32_e32 v136, v76
	v_mov_b32_e32 v137, v72
	v_pk_fma_f32 v[134:135], v[136:137], v[136:137], v[134:135]
	v_mov_b32_e32 v136, v77
	v_mov_b32_e32 v137, v73
	s_waitcnt lgkmcnt(0)
	v_pk_add_f32 v[124:125], v[124:125], v[126:127]
	v_pk_fma_f32 v[134:135], v[136:137], v[136:137], v[134:135]
	v_mov_b32_e32 v136, v78
	v_mov_b32_e32 v137, v74
	v_mov_b32_e32 v127, v125
	v_mov_b32_e32 v126, v124
	s_nop 1
	v_permlane16_swap_b32 v125, v127
	v_permlane16_swap_b32 v124, v126
	v_pk_mul_f32 v[132:133], v[56:57], v[56:57]
	s_waitcnt vmcnt(0)
	v_pk_mul_f32 v[140:141], v[60:61], v[60:61]
	v_pk_fma_f32 v[134:135], v[136:137], v[136:137], v[134:135]
	v_mov_b32_e32 v136, v79
	v_mov_b32_e32 v137, v75
	v_pk_fma_f32 v[134:135], v[136:137], v[136:137], v[134:135]
	v_mov_b32_e32 v136, v140
	v_mov_b32_e32 v137, v132
	v_pk_mul_f32 v[130:131], v[58:59], v[58:59]
	v_pk_mul_f32 v[138:139], v[62:63], v[62:63]
	v_pk_add_f32 v[134:135], v[136:137], v[134:135]
	v_mov_b32_e32 v132, v141
	v_pk_add_f32 v[132:133], v[132:133], v[134:135]
	v_mov_b32_e32 v134, v138
	v_mov_b32_e32 v135, v130
	v_pk_add_f32 v[132:133], v[134:135], v[132:133]
	v_mov_b32_e32 v130, v139
	s_waitcnt lgkmcnt(0)
	v_pk_add_f32 v[124:125], v[124:125], v[126:127]
	v_pk_add_f32 v[130:131], v[130:131], v[132:133]
	s_nop 1
	v_mov_b32_dpp v127, v125 row_ror:8 row_mask:0xf bank_mask:0xf
	v_mov_b32_dpp v126, v124 row_ror:8 row_mask:0xf bank_mask:0xf
	v_mov_b32_e32 v133, v131
	v_mov_b32_e32 v132, v130
	s_nop 1
	v_permlane32_swap_b32 v131, v133
	v_permlane32_swap_b32 v130, v132
	v_pk_add_f32 v[136:137], v[18:19], 1.0 op_sel_hi:[1,0]
	v_lshl_add_u64 v[112:113], v[112:113], 0, 4
	s_waitcnt lgkmcnt(0)
	v_pk_add_f32 v[124:125], v[124:125], v[126:127]
	s_nop 1
	v_mov_b32_dpp v127, v125 row_shl:4 row_mask:0xf bank_mask:0x5
	v_mov_b32_dpp v127, v125 row_shr:4 row_mask:0xf bank_mask:0xa
	s_waitcnt lgkmcnt(0)
	v_pk_add_f32 v[130:131], v[130:131], v[132:133]
	s_nop 1
	v_mov_b32_dpp v126, v124 row_shl:4 row_mask:0xf bank_mask:0x5
	v_mov_b32_dpp v126, v124 row_shr:4 row_mask:0xf bank_mask:0xa
	v_mov_b32_e32 v133, v131
	v_mov_b32_e32 v132, v130
	s_nop 1
	v_permlane16_swap_b32 v131, v133
	v_permlane16_swap_b32 v130, v132
	s_waitcnt lgkmcnt(0)
	v_pk_add_f32 v[124:125], v[124:125], v[126:127]
	s_nop 1
	v_mov_b32_dpp v127, v125 quad_perm:[2,3,0,1] row_mask:0xf bank_mask:0xf
	s_waitcnt lgkmcnt(0)
	v_pk_add_f32 v[130:131], v[130:131], v[132:133]
	s_nop 1
	v_mov_b32_dpp v126, v124 quad_perm:[2,3,0,1] row_mask:0xf bank_mask:0xf
	s_nop 1
	v_mov_b32_dpp v133, v131 row_ror:8 row_mask:0xf bank_mask:0xf
	v_mov_b32_dpp v132, v130 row_ror:8 row_mask:0xf bank_mask:0xf
	s_waitcnt lgkmcnt(0)
	v_pk_add_f32 v[124:125], v[124:125], v[126:127]
	s_nop 1
	v_mov_b32_dpp v127, v125 quad_perm:[1,0,3,2] row_mask:0xf bank_mask:0xf
	s_waitcnt lgkmcnt(0)
	v_pk_add_f32 v[130:131], v[130:131], v[132:133]
	s_nop 1
	v_mov_b32_dpp v126, v124 quad_perm:[1,0,3,2] row_mask:0xf bank_mask:0xf
	s_nop 1
	v_mov_b32_dpp v133, v131 row_shl:4 row_mask:0xf bank_mask:0x5
	v_mov_b32_dpp v132, v130 row_shl:4 row_mask:0xf bank_mask:0x5
	v_mov_b32_dpp v133, v131 row_shr:4 row_mask:0xf bank_mask:0xa
	v_mov_b32_dpp v132, v130 row_shr:4 row_mask:0xf bank_mask:0xa
	s_waitcnt lgkmcnt(0)
	v_pk_add_f32 v[124:125], v[124:125], v[126:127]
	v_mov_b64_e32 v[126:127], s[18:19]
	s_waitcnt lgkmcnt(0)
	v_pk_add_f32 v[130:131], v[130:131], v[132:133]
	v_pk_fma_f32 v[124:125], v[124:125], s[16:17], v[126:127] op_sel_hi:[1,0,0]
	s_nop 1
	v_mov_b32_dpp v133, v131 quad_perm:[2,3,0,1] row_mask:0xf bank_mask:0xf
	v_mov_b32_dpp v132, v130 quad_perm:[2,3,0,1] row_mask:0xf bank_mask:0xf
	v_mul_f32_e32 v134, 0x4b800000, v125
	v_cmp_gt_f32_e32 vcc, s19, v125
	v_cmp_gt_f32_e64 s[0:1], s19, v124
	s_nop 0
	v_cndmask_b32_e32 v125, v125, v134, vcc
	v_rsq_f32_e32 v134, v125
	v_mul_f32_e32 v125, 0x4b800000, v124
	v_cndmask_b32_e64 v124, v124, v125, s[0:1]
	v_rsq_f32_e32 v135, v124
	s_waitcnt lgkmcnt(0)
	v_pk_add_f32 v[124:125], v[130:131], v[132:133]
	s_nop 1
	v_mov_b32_dpp v131, v125 quad_perm:[1,0,3,2] row_mask:0xf bank_mask:0xf
	v_mov_b32_dpp v130, v124 quad_perm:[1,0,3,2] row_mask:0xf bank_mask:0xf
	v_mul_f32_e32 v132, 0x45800000, v134
	v_cndmask_b32_e32 v132, v134, v132, vcc
	v_mul_f32_e32 v133, 0x45800000, v135
	v_pk_mul_f32 v[100:101], v[100:101], v[132:133] op_sel_hi:[1,0]
	s_waitcnt lgkmcnt(0)
	v_pk_add_f32 v[124:125], v[124:125], v[130:131]
	v_pk_mul_f32 v[102:103], v[102:103], v[132:133] op_sel_hi:[1,0]
	v_pk_fma_f32 v[124:125], v[124:125], s[16:17], v[126:127] op_sel_hi:[1,0,0]
	v_pk_mul_f32 v[100:101], v[12:13], v[100:101]
	v_mul_f32_e32 v126, 0x4b800000, v125
	v_cmp_gt_f32_e32 vcc, s19, v125
	v_cmp_gt_f32_e64 s[4:5], s19, v124
	v_pk_mul_f32 v[102:103], v[14:15], v[102:103]
	v_cndmask_b32_e32 v125, v125, v126, vcc
	v_mul_f32_e32 v126, 0x4b800000, v124
	v_rsq_f32_e32 v125, v125
	v_cndmask_b32_e64 v124, v124, v126, s[4:5]
	v_rsq_f32_e32 v127, v124
	v_cndmask_b32_e64 v124, v135, v133, s[0:1]
	v_mul_f32_e32 v126, 0x45800000, v125
	v_cndmask_b32_e32 v126, v125, v126, vcc
	v_mul_f32_e32 v125, 0x45800000, v127
	v_pk_add_f32 v[134:135], v[16:17], 1.0 op_sel_hi:[1,0]
	v_pk_mul_f32 v[96:97], v[96:97], v[124:125] op_sel_hi:[1,0]
	v_pk_mul_f32 v[98:99], v[98:99], v[124:125] op_sel_hi:[1,0]
	v_pk_fma_f32 v[100:101], v[134:135], v[100:101], v[20:21]
	v_pk_fma_f32 v[102:103], v[136:137], v[102:103], v[22:23]
	v_pk_mul_f32 v[96:97], v[12:13], v[96:97]
	v_pk_mul_f32 v[98:99], v[14:15], v[98:99]
	v_cvt_pk_bf16_f32 v100, v100, v101
	v_cvt_pk_bf16_f32 v101, v102, v103
	v_add_co_u32_e32 v102, vcc, s22, v114
	v_pk_fma_f32 v[96:97], v[134:135], v[96:97], v[20:21]
	v_pk_fma_f32 v[98:99], v[136:137], v[98:99], v[22:23]
	v_addc_co_u32_e32 v103, vcc, -1, v115, vcc
	v_cvt_pk_bf16_f32 v96, v96, v97
	v_cvt_pk_bf16_f32 v97, v98, v99
	global_store_dwordx2 v[102:103], v[96:97], off offset:-1536
	v_pk_mul_f32 v[96:97], v[104:105], v[126:127] op_sel_hi:[1,0]
	v_pk_mul_f32 v[98:99], v[106:107], v[126:127] op_sel_hi:[1,0]
	v_pk_mul_f32 v[96:97], v[12:13], v[96:97]
	v_pk_mul_f32 v[98:99], v[14:15], v[98:99]
	v_pk_fma_f32 v[96:97], v[134:135], v[96:97], v[20:21]
	v_pk_fma_f32 v[98:99], v[136:137], v[98:99], v[22:23]
	v_cndmask_b32_e64 v130, v127, v125, s[4:5]
	v_cvt_pk_bf16_f32 v96, v96, v97
	v_cvt_pk_bf16_f32 v97, v98, v99
	global_store_dwordx2 v[114:115], v[96:97], off offset:-3584
	v_pk_mul_f32 v[96:97], v[108:109], v[130:131] op_sel_hi:[1,0]
	v_pk_mul_f32 v[98:99], v[110:111], v[130:131] op_sel_hi:[1,0]
	v_pk_mul_f32 v[96:97], v[12:13], v[96:97]
	v_pk_mul_f32 v[98:99], v[14:15], v[98:99]
	v_pk_fma_f32 v[96:97], v[134:135], v[96:97], v[20:21]
	v_pk_fma_f32 v[98:99], v[136:137], v[98:99], v[22:23]
	v_cvt_pk_bf16_f32 v96, v96, v97
	v_cvt_pk_bf16_f32 v97, v98, v99
	v_pk_mul_f32 v[80:81], v[80:81], v[132:133] op_sel_hi:[1,0]
	v_pk_mul_f32 v[82:83], v[82:83], v[132:133] op_sel_hi:[1,0]
	global_store_dwordx2 v[114:115], v[96:97], off offset:-1536
	v_pk_mul_f32 v[80:81], v[8:9], v[80:81]
	v_pk_add_f32 v[96:97], v[28:29], 1.0 op_sel_hi:[1,0]
	v_pk_mul_f32 v[82:83], v[10:11], v[82:83]
	v_pk_add_f32 v[98:99], v[30:31], 1.0 op_sel_hi:[1,0]
	v_pk_fma_f32 v[80:81], v[96:97], v[80:81], v[24:25]
	v_pk_fma_f32 v[82:83], v[98:99], v[82:83], v[26:27]
	v_cvt_pk_bf16_f32 v80, v80, v81
	v_cvt_pk_bf16_f32 v81, v82, v83
	global_store_dwordx2 v[102:103], v[80:81], off offset:-3072
	v_pk_mul_f32 v[80:81], v[84:85], v[124:125] op_sel_hi:[1,0]
	v_pk_mul_f32 v[82:83], v[86:87], v[124:125] op_sel_hi:[1,0]
	v_pk_mul_f32 v[80:81], v[8:9], v[80:81]
	v_pk_mul_f32 v[82:83], v[10:11], v[82:83]
	v_pk_fma_f32 v[80:81], v[96:97], v[80:81], v[24:25]
	v_pk_fma_f32 v[82:83], v[98:99], v[82:83], v[26:27]
	v_cvt_pk_bf16_f32 v80, v80, v81
	v_cvt_pk_bf16_f32 v81, v82, v83
	global_store_dwordx2 v[102:103], v[80:81], off offset:-1024
	v_pk_mul_f32 v[80:81], v[88:89], v[126:127] op_sel_hi:[1,0]
	v_pk_mul_f32 v[82:83], v[90:91], v[126:127] op_sel_hi:[1,0]
	v_pk_mul_f32 v[80:81], v[8:9], v[80:81]
	v_pk_mul_f32 v[82:83], v[10:11], v[82:83]
	v_pk_fma_f32 v[80:81], v[96:97], v[80:81], v[24:25]
	v_pk_fma_f32 v[82:83], v[98:99], v[82:83], v[26:27]
	v_cvt_pk_bf16_f32 v80, v80, v81
	v_cvt_pk_bf16_f32 v81, v82, v83
	global_store_dwordx2 v[114:115], v[80:81], off offset:-3072
	v_pk_mul_f32 v[80:81], v[92:93], v[130:131] op_sel_hi:[1,0]
	v_pk_mul_f32 v[82:83], v[94:95], v[130:131] op_sel_hi:[1,0]
	v_pk_mul_f32 v[80:81], v[8:9], v[80:81]
	v_pk_mul_f32 v[82:83], v[10:11], v[82:83]
	v_pk_fma_f32 v[80:81], v[96:97], v[80:81], v[24:25]
	v_pk_fma_f32 v[82:83], v[98:99], v[82:83], v[26:27]
	v_cvt_pk_bf16_f32 v80, v80, v81
	v_cvt_pk_bf16_f32 v81, v82, v83
	v_pk_mul_f32 v[64:65], v[64:65], v[132:133] op_sel_hi:[1,0]
	v_pk_mul_f32 v[66:67], v[66:67], v[132:133] op_sel_hi:[1,0]
	global_store_dwordx2 v[114:115], v[80:81], off offset:-1024
	v_pk_mul_f32 v[64:65], v[4:5], v[64:65]
	v_pk_add_f32 v[80:81], v[36:37], 1.0 op_sel_hi:[1,0]
	v_pk_mul_f32 v[66:67], v[6:7], v[66:67]
	v_pk_add_f32 v[82:83], v[38:39], 1.0 op_sel_hi:[1,0]
	v_pk_fma_f32 v[64:65], v[80:81], v[64:65], v[32:33]
	v_pk_fma_f32 v[66:67], v[82:83], v[66:67], v[34:35]
	v_cvt_pk_bf16_f32 v64, v64, v65
	v_cvt_pk_bf16_f32 v65, v66, v67
	global_store_dwordx2 v[102:103], v[64:65], off offset:-2560
	v_pk_mul_f32 v[64:65], v[68:69], v[124:125] op_sel_hi:[1,0]
	v_pk_mul_f32 v[66:67], v[70:71], v[124:125] op_sel_hi:[1,0]
	v_pk_mul_f32 v[64:65], v[4:5], v[64:65]
	v_pk_mul_f32 v[66:67], v[6:7], v[66:67]
	v_pk_fma_f32 v[64:65], v[80:81], v[64:65], v[32:33]
	v_pk_fma_f32 v[66:67], v[82:83], v[66:67], v[34:35]
	v_cvt_pk_bf16_f32 v64, v64, v65
	v_cvt_pk_bf16_f32 v65, v66, v67
	global_store_dwordx2 v[102:103], v[64:65], off offset:-512
	v_pk_mul_f32 v[64:65], v[72:73], v[126:127] op_sel_hi:[1,0]
	v_pk_mul_f32 v[66:67], v[74:75], v[126:127] op_sel_hi:[1,0]
	v_pk_mul_f32 v[64:65], v[4:5], v[64:65]
	v_pk_mul_f32 v[66:67], v[6:7], v[66:67]
	v_pk_fma_f32 v[64:65], v[80:81], v[64:65], v[32:33]
	v_pk_fma_f32 v[66:67], v[82:83], v[66:67], v[34:35]
	v_cvt_pk_bf16_f32 v64, v64, v65
	v_cvt_pk_bf16_f32 v65, v66, v67
	global_store_dwordx2 v[114:115], v[64:65], off offset:-2560
	v_pk_mul_f32 v[64:65], v[76:77], v[130:131] op_sel_hi:[1,0]
	v_pk_mul_f32 v[66:67], v[78:79], v[130:131] op_sel_hi:[1,0]
	v_pk_mul_f32 v[64:65], v[4:5], v[64:65]
	v_pk_mul_f32 v[66:67], v[6:7], v[66:67]
	v_pk_fma_f32 v[64:65], v[80:81], v[64:65], v[32:33]
	v_pk_fma_f32 v[66:67], v[82:83], v[66:67], v[34:35]
	v_cvt_pk_bf16_f32 v64, v64, v65
	v_cvt_pk_bf16_f32 v65, v66, v67
	v_pk_mul_f32 v[48:49], v[48:49], v[132:133] op_sel_hi:[1,0]
	v_pk_mul_f32 v[50:51], v[50:51], v[132:133] op_sel_hi:[1,0]
	global_store_dwordx2 v[114:115], v[64:65], off offset:-512
	v_pk_mul_f32 v[48:49], v[0:1], v[48:49]
	v_pk_add_f32 v[64:65], v[44:45], 1.0 op_sel_hi:[1,0]
	v_pk_mul_f32 v[50:51], v[2:3], v[50:51]
	v_pk_add_f32 v[66:67], v[46:47], 1.0 op_sel_hi:[1,0]
	v_pk_fma_f32 v[48:49], v[64:65], v[48:49], v[40:41]
	v_pk_fma_f32 v[50:51], v[66:67], v[50:51], v[42:43]
	v_cvt_pk_bf16_f32 v48, v48, v49
	v_cvt_pk_bf16_f32 v49, v50, v51
	global_store_dwordx2 v[102:103], v[48:49], off offset:-2048
	v_pk_mul_f32 v[48:49], v[52:53], v[124:125] op_sel_hi:[1,0]
	v_pk_mul_f32 v[50:51], v[54:55], v[124:125] op_sel_hi:[1,0]
	v_pk_mul_f32 v[48:49], v[0:1], v[48:49]
	v_pk_mul_f32 v[50:51], v[2:3], v[50:51]
	v_pk_fma_f32 v[48:49], v[64:65], v[48:49], v[40:41]
	v_pk_fma_f32 v[50:51], v[66:67], v[50:51], v[42:43]
	v_cvt_pk_bf16_f32 v48, v48, v49
	v_cvt_pk_bf16_f32 v49, v50, v51
	global_store_dwordx2 v[114:115], v[48:49], off offset:-4096
	v_pk_mul_f32 v[48:49], v[56:57], v[126:127] op_sel_hi:[1,0]
	v_pk_mul_f32 v[50:51], v[58:59], v[126:127] op_sel_hi:[1,0]
	v_pk_mul_f32 v[48:49], v[0:1], v[48:49]
	v_pk_mul_f32 v[50:51], v[2:3], v[50:51]
	v_pk_fma_f32 v[48:49], v[64:65], v[48:49], v[40:41]
	v_pk_fma_f32 v[50:51], v[66:67], v[50:51], v[42:43]
	v_cvt_pk_bf16_f32 v48, v48, v49
	v_cvt_pk_bf16_f32 v49, v50, v51
	global_store_dwordx2 v[114:115], v[48:49], off offset:-2048
	v_pk_mul_f32 v[48:49], v[60:61], v[130:131] op_sel_hi:[1,0]
	v_pk_mul_f32 v[50:51], v[62:63], v[130:131] op_sel_hi:[1,0]
	v_pk_mul_f32 v[48:49], v[0:1], v[48:49]
	v_pk_mul_f32 v[50:51], v[2:3], v[50:51]
	v_pk_fma_f32 v[48:49], v[64:65], v[48:49], v[40:41]
	v_pk_fma_f32 v[50:51], v[66:67], v[50:51], v[42:43]
	v_cvt_pk_bf16_f32 v48, v48, v49
	v_cvt_pk_bf16_f32 v49, v50, v51
	global_store_dwordx2 v[114:115], v[48:49], off
	v_add_u32_e32 v48, -1, v112
	v_cmp_ge_i32_e32 vcc, v48, v116
	s_or_b64 s[8:9], vcc, s[8:9]
	v_lshl_add_u64 v[114:115], v[114:115], 0, s[20:21]
	global_store_dwordx2 v[102:103], v[100:101], off offset:-3584
	s_andn2_b64 exec, exec, s[8:9]
	s_cbranch_execz .LBB0_76

.LBB0_321:
	s_or_b64 exec, exec, s[0:1]
	s_waitcnt vmcnt(3)
	v_and_b32_e32 v159, 0xffff0000, v156
	v_and_b32_e32 v191, 0xffff0000, v136
	v_lshlrev_b32_e32 v158, 16, v156
	v_lshlrev_b32_e32 v190, 16, v136
	v_mov_b32_e32 v206, v159
	v_mov_b32_e32 v207, v191
	v_lshlrev_b32_e32 v156, 16, v157
	v_lshlrev_b32_e32 v136, 16, v137
	v_mov_b32_e32 v204, v158
	v_mov_b32_e32 v205, v190
	v_pk_mul_f32 v[206:207], v[206:207], v[206:207]
	v_and_b32_e32 v157, 0xffff0000, v157
	v_and_b32_e32 v137, 0xffff0000, v137
	v_pk_fma_f32 v[204:205], v[204:205], v[204:205], v[206:207]
	v_mov_b32_e32 v206, v156
	v_mov_b32_e32 v207, v136
	s_waitcnt vmcnt(2)
	v_lshlrev_b32_e32 v176, 16, v142
	v_lshlrev_b32_e32 v192, 16, v134
	v_pk_fma_f32 v[204:205], v[206:207], v[206:207], v[204:205]
	v_mov_b32_e32 v206, v157
	v_mov_b32_e32 v207, v137
	v_and_b32_e32 v177, 0xffff0000, v142
	v_and_b32_e32 v193, 0xffff0000, v134
	v_pk_fma_f32 v[204:205], v[206:207], v[206:207], v[204:205]
	v_mov_b32_e32 v206, v176
	v_mov_b32_e32 v207, v192
	v_lshlrev_b32_e32 v142, 16, v143
	v_lshlrev_b32_e32 v134, 16, v135
	v_pk_fma_f32 v[204:205], v[206:207], v[206:207], v[204:205]
	v_mov_b32_e32 v206, v177
	v_mov_b32_e32 v207, v193
	v_and_b32_e32 v143, 0xffff0000, v143
	v_and_b32_e32 v135, 0xffff0000, v135
	v_pk_fma_f32 v[204:205], v[206:207], v[206:207], v[204:205]
	v_mov_b32_e32 v206, v142
	v_mov_b32_e32 v207, v134
	s_waitcnt vmcnt(1)
	v_lshlrev_b32_e32 v178, 16, v138
	v_lshlrev_b32_e32 v196, 16, v132
	v_pk_fma_f32 v[204:205], v[206:207], v[206:207], v[204:205]
	v_mov_b32_e32 v206, v143
	v_mov_b32_e32 v207, v135
	v_and_b32_e32 v179, 0xffff0000, v138
	v_and_b32_e32 v197, 0xffff0000, v132
	v_pk_fma_f32 v[204:205], v[206:207], v[206:207], v[204:205]
	v_mov_b32_e32 v206, v178
	v_mov_b32_e32 v207, v196
	v_lshlrev_b32_e32 v188, 16, v139
	v_lshlrev_b32_e32 v132, 16, v133
	v_pk_fma_f32 v[204:205], v[206:207], v[206:207], v[204:205]
	v_mov_b32_e32 v206, v179
	v_mov_b32_e32 v207, v197
	v_and_b32_e32 v189, 0xffff0000, v139
	s_waitcnt vmcnt(0)
	v_lshlrev_b32_e32 v138, 16, v140
	v_and_b32_e32 v139, 0xffff0000, v140
	v_and_b32_e32 v133, 0xffff0000, v133
	v_lshlrev_b32_e32 v198, 16, v130
	v_and_b32_e32 v199, 0xffff0000, v130
	v_pk_fma_f32 v[204:205], v[206:207], v[206:207], v[204:205]
	v_mov_b32_e32 v206, v188
	v_mov_b32_e32 v207, v132
	v_lshlrev_b32_e32 v200, 16, v131
	v_and_b32_e32 v201, 0xffff0000, v131
	v_pk_mul_f32 v[130:131], v[198:199], v[198:199]
	v_pk_mul_f32 v[208:209], v[138:139], v[138:139]
	v_pk_fma_f32 v[204:205], v[206:207], v[206:207], v[204:205]
	v_mov_b32_e32 v206, v189
	v_mov_b32_e32 v207, v133
	v_lshlrev_b32_e32 v140, 16, v141
	v_and_b32_e32 v141, 0xffff0000, v141
	v_pk_fma_f32 v[204:205], v[206:207], v[206:207], v[204:205]
	v_mov_b32_e32 v206, v208
	v_mov_b32_e32 v207, v130
	v_pk_mul_f32 v[202:203], v[200:201], v[200:201]
	v_pk_add_f32 v[204:205], v[206:207], v[204:205]
	v_pk_mul_f32 v[206:207], v[140:141], v[140:141]
	v_mov_b32_e32 v130, v209
	v_pk_add_f32 v[130:131], v[130:131], v[204:205]
	v_mov_b32_e32 v204, v206
	v_mov_b32_e32 v205, v202
	v_pk_add_f32 v[130:131], v[204:205], v[130:131]
	v_mov_b32_e32 v202, v207
	v_pk_add_f32 v[130:131], v[202:203], v[130:131]
	v_mov_b32_e32 v203, v131
	v_mov_b32_e32 v202, v130
	s_nop 1
	v_permlane32_swap_b32 v131, v203
	v_permlane32_swap_b32 v130, v202
	v_pk_mul_f32 v[206:207], v[40:41], 0.5 op_sel_hi:[1,0]
	v_lshl_add_u64 v[118:119], v[118:119], 0, 2
	v_lshl_add_u64 v[116:117], v[116:117], 0, s[18:19]
	s_waitcnt lgkmcnt(0)
	v_pk_add_f32 v[130:131], v[130:131], v[202:203]
	v_mov_b32_e32 v203, v131
	v_mov_b32_e32 v202, v130
	s_nop 1
	v_permlane16_swap_b32 v131, v203
	v_permlane16_swap_b32 v130, v202
	s_waitcnt lgkmcnt(0)
	v_pk_add_f32 v[130:131], v[130:131], v[202:203]
	s_nop 1
	v_mov_b32_dpp v203, v131 row_ror:8 row_mask:0xf bank_mask:0xf
	v_mov_b32_dpp v202, v130 row_ror:8 row_mask:0xf bank_mask:0xf
	s_waitcnt lgkmcnt(0)
	v_pk_add_f32 v[130:131], v[130:131], v[202:203]
	s_nop 1
	v_mov_b32_dpp v203, v131 row_shl:4 row_mask:0xf bank_mask:0x5
	v_mov_b32_dpp v202, v130 row_shl:4 row_mask:0xf bank_mask:0x5
	v_mov_b32_dpp v203, v131 row_shr:4 row_mask:0xf bank_mask:0xa
	v_mov_b32_dpp v202, v130 row_shr:4 row_mask:0xf bank_mask:0xa
	s_waitcnt lgkmcnt(0)
	v_pk_add_f32 v[130:131], v[130:131], v[202:203]
	s_nop 1
	v_mov_b32_dpp v203, v131 quad_perm:[2,3,0,1] row_mask:0xf bank_mask:0xf
	v_mov_b32_dpp v202, v130 quad_perm:[2,3,0,1] row_mask:0xf bank_mask:0xf
	s_waitcnt lgkmcnt(0)
	v_pk_add_f32 v[130:131], v[130:131], v[202:203]
	s_nop 1
	v_mov_b32_dpp v203, v131 quad_perm:[1,0,3,2] row_mask:0xf bank_mask:0xf
	v_mov_b32_dpp v202, v130 quad_perm:[1,0,3,2] row_mask:0xf bank_mask:0xf
	s_waitcnt lgkmcnt(0)
	v_pk_add_f32 v[202:203], v[130:131], v[202:203]
	v_mov_b64_e32 v[130:131], s[38:39]
	v_pk_fma_f32 v[202:203], v[202:203], s[24:25], v[130:131] op_sel_hi:[1,0,0]
	s_nop 0
	v_mul_f32_e32 v153, 0x4b800000, v203
	v_cmp_gt_f32_e32 vcc, s5, v203
	v_mul_f32_e32 v155, 0x4b800000, v202
	v_cmp_gt_f32_e64 s[0:1], s5, v202
	v_cndmask_b32_e32 v153, v203, v153, vcc
	v_rsq_f32_e32 v153, v153
	v_cndmask_b32_e64 v155, v202, v155, s[0:1]
	v_rsq_f32_e32 v155, v155
	v_mul_f32_e32 v175, 0x45800000, v153
	v_cndmask_b32_e32 v202, v153, v175, vcc
	v_pk_mul_f32 v[190:191], v[202:203], v[190:191] op_sel_hi:[0,1]
	v_pk_mul_f32 v[190:191], v[28:29], v[190:191]
	v_pk_mul_f32 v[136:137], v[202:203], v[136:137] op_sel_hi:[0,1]
	v_mul_f32_e32 v153, 0x45800000, v155
	v_pk_fma_f32 v[100:101], v[206:207], v[190:191], v[100:101]
	v_pk_mul_f32 v[190:191], v[42:43], 0.5 op_sel_hi:[1,0]
	v_pk_mul_f32 v[136:137], v[30:31], v[136:137]
	v_cndmask_b32_e64 v204, v155, v153, s[0:1]
	v_pk_fma_f32 v[102:103], v[190:191], v[136:137], v[102:103]
	v_pk_mul_f32 v[134:135], v[202:203], v[134:135] op_sel_hi:[0,1]
	v_cvt_pk_bf16_f32 v137, v102, v103
	v_pk_mul_f32 v[102:103], v[204:205], v[158:159] op_sel_hi:[0,1]
	v_pk_mul_f32 v[102:103], v[28:29], v[102:103]
	v_pk_mul_f32 v[134:135], v[26:27], v[134:135]
	v_pk_fma_f32 v[102:103], v[206:207], v[102:103], v[108:109]
	v_pk_mul_f32 v[108:109], v[204:205], v[156:157] op_sel_hi:[0,1]
	v_pk_mul_f32 v[108:109], v[30:31], v[108:109]
	v_pk_mul_f32 v[156:157], v[202:203], v[192:193] op_sel_hi:[0,1]
	v_pk_fma_f32 v[108:109], v[190:191], v[108:109], v[110:111]
	v_pk_mul_f32 v[156:157], v[24:25], v[156:157]
	v_cvt_pk_bf16_f32 v111, v108, v109
	v_pk_mul_f32 v[108:109], v[52:53], 0.5 op_sel_hi:[1,0]
	v_cvt_pk_bf16_f32 v136, v100, v101
	v_pk_fma_f32 v[92:93], v[108:109], v[156:157], v[92:93]
	v_pk_mul_f32 v[156:157], v[54:55], 0.5 op_sel_hi:[1,0]
	v_cvt_pk_bf16_f32 v92, v92, v93
	v_pk_fma_f32 v[94:95], v[156:157], v[134:135], v[94:95]
	v_cvt_pk_bf16_f32 v110, v102, v103
	v_cvt_pk_bf16_f32 v93, v94, v95
	v_pk_mul_f32 v[94:95], v[204:205], v[176:177] op_sel_hi:[0,1]
	v_pk_mul_f32 v[94:95], v[24:25], v[94:95]
	v_lshl_add_u64 v[100:101], v[114:115], 0, v[124:125]
	v_pk_fma_f32 v[94:95], v[108:109], v[94:95], v[104:105]
	v_pk_mul_f32 v[104:105], v[204:205], v[142:143] op_sel_hi:[0,1]
	v_pk_mul_f32 v[104:105], v[26:27], v[104:105]
	v_cvt_pk_bf16_f32 v94, v94, v95
	v_pk_fma_f32 v[104:105], v[156:157], v[104:105], v[106:107]
	v_pk_mul_f32 v[106:107], v[202:203], v[196:197] op_sel_hi:[0,1]
	v_cvt_pk_bf16_f32 v95, v104, v105
	v_pk_mul_f32 v[104:105], v[64:65], 0.5 op_sel_hi:[1,0]
	v_pk_mul_f32 v[106:107], v[12:13], v[106:107]
	v_pk_mul_f32 v[108:109], v[202:203], v[132:133] op_sel_hi:[0,1]
	v_pk_fma_f32 v[84:85], v[104:105], v[106:107], v[84:85]
	v_pk_mul_f32 v[106:107], v[66:67], 0.5 op_sel_hi:[1,0]
	v_pk_mul_f32 v[108:109], v[14:15], v[108:109]
	v_cvt_pk_bf16_f32 v84, v84, v85
	v_pk_fma_f32 v[86:87], v[106:107], v[108:109], v[86:87]
	v_lshl_add_u64 v[102:103], v[114:115], 0, v[126:127]
	v_cvt_pk_bf16_f32 v85, v86, v87
	v_pk_mul_f32 v[86:87], v[204:205], v[178:179] op_sel_hi:[0,1]
	v_pk_mul_f32 v[86:87], v[12:13], v[86:87]
	global_store_dwordx2 v[100:101], v[136:137], off
	v_pk_fma_f32 v[86:87], v[104:105], v[86:87], v[96:97]
	v_pk_mul_f32 v[96:97], v[204:205], v[188:189] op_sel_hi:[0,1]
	v_pk_mul_f32 v[96:97], v[14:15], v[96:97]
	v_cvt_pk_bf16_f32 v86, v86, v87
	v_pk_fma_f32 v[96:97], v[106:107], v[96:97], v[98:99]
	v_pk_mul_f32 v[98:99], v[202:203], v[198:199] op_sel_hi:[0,1]
	v_cvt_pk_bf16_f32 v87, v96, v97
	v_pk_mul_f32 v[96:97], v[68:69], 0.5 op_sel_hi:[1,0]
	v_pk_mul_f32 v[98:99], v[8:9], v[98:99]
	v_pk_mul_f32 v[104:105], v[202:203], v[200:201] op_sel_hi:[0,1]
	v_pk_fma_f32 v[80:81], v[96:97], v[98:99], v[80:81]
	v_pk_mul_f32 v[98:99], v[70:71], 0.5 op_sel_hi:[1,0]
	v_pk_mul_f32 v[104:105], v[10:11], v[104:105]
	global_store_dwordx2 v[102:103], v[110:111], off
	v_pk_fma_f32 v[82:83], v[98:99], v[104:105], v[82:83]
	v_cvt_pk_bf16_f32 v104, v80, v81
	v_cvt_pk_bf16_f32 v105, v82, v83
	v_pk_mul_f32 v[82:83], v[204:205], v[140:141] op_sel_hi:[0,1]
	v_pk_mul_f32 v[80:81], v[204:205], v[138:139] op_sel_hi:[0,1]
	v_pk_mul_f32 v[82:83], v[10:11], v[82:83]
	v_pk_mul_f32 v[80:81], v[8:9], v[80:81]
	v_pk_fma_f32 v[82:83], v[98:99], v[82:83], v[90:91]
	v_pk_fma_f32 v[80:81], v[96:97], v[80:81], v[88:89]
	v_cvt_pk_bf16_f32 v89, v82, v83
	v_and_b32_e32 v97, 0xffff0000, v136
	v_and_b32_e32 v83, 0xffff0000, v110
	v_lshlrev_b32_e32 v96, 16, v136
	v_lshlrev_b32_e32 v82, 16, v110
	v_mov_b32_e32 v108, v83
	v_mov_b32_e32 v109, v97
	v_cvt_pk_bf16_f32 v88, v80, v81
	v_lshlrev_b32_e32 v90, 16, v137
	v_lshlrev_b32_e32 v80, 16, v111
	v_mov_b32_e32 v106, v82
	v_mov_b32_e32 v107, v96
	v_pk_mul_f32 v[108:109], v[108:109], v[108:109]
	v_and_b32_e32 v91, 0xffff0000, v137
	v_and_b32_e32 v81, 0xffff0000, v111
	v_mov_b32_e32 v98, v80
	v_mov_b32_e32 v99, v90
	v_pk_fma_f32 v[106:107], v[106:107], v[106:107], v[108:109]
	v_lshlrev_b32_e32 v110, 16, v92
	v_lshlrev_b32_e32 v134, 16, v94
	v_mov_b32_e32 v198, v81
	v_mov_b32_e32 v199, v91
	v_pk_fma_f32 v[98:99], v[98:99], v[98:99], v[106:107]
	v_and_b32_e32 v111, 0xffff0000, v92
	v_and_b32_e32 v135, 0xffff0000, v94
	v_pk_fma_f32 v[98:99], v[198:199], v[198:199], v[98:99]
	v_mov_b32_e32 v200, v134
	v_mov_b32_e32 v201, v110
	v_lshlrev_b32_e32 v108, 16, v93
	v_lshlrev_b32_e32 v132, 16, v95
	v_mov_b32_e32 v202, v135
	v_mov_b32_e32 v203, v111
	v_pk_fma_f32 v[98:99], v[200:201], v[200:201], v[98:99]
	v_and_b32_e32 v109, 0xffff0000, v93
	v_and_b32_e32 v133, 0xffff0000, v95
	v_mov_b32_e32 v106, v132
	v_mov_b32_e32 v107, v108
	v_pk_fma_f32 v[98:99], v[202:203], v[202:203], v[98:99]
	v_lshlrev_b32_e32 v138, 16, v84
	v_lshlrev_b32_e32 v142, 16, v86
	v_mov_b32_e32 v198, v133
	v_mov_b32_e32 v199, v109
	v_pk_fma_f32 v[98:99], v[106:107], v[106:107], v[98:99]
	v_and_b32_e32 v139, 0xffff0000, v84
	v_and_b32_e32 v143, 0xffff0000, v86
	v_pk_fma_f32 v[98:99], v[198:199], v[198:199], v[98:99]
	v_mov_b32_e32 v200, v142
	v_mov_b32_e32 v201, v138
	v_lshlrev_b32_e32 v136, 16, v85
	v_lshlrev_b32_e32 v140, 16, v87
	v_mov_b32_e32 v202, v143
	v_mov_b32_e32 v203, v139
	v_pk_fma_f32 v[98:99], v[200:201], v[200:201], v[98:99]
	v_and_b32_e32 v137, 0xffff0000, v85
	v_and_b32_e32 v141, 0xffff0000, v87
	v_lshlrev_b32_e32 v176, 16, v104
	v_and_b32_e32 v177, 0xffff0000, v104
	v_lshlrev_b32_e32 v192, 16, v88
	v_and_b32_e32 v193, 0xffff0000, v88
	v_mov_b32_e32 v106, v140
	v_mov_b32_e32 v107, v136
	v_pk_fma_f32 v[98:99], v[202:203], v[202:203], v[98:99]
	v_pk_mul_f32 v[178:179], v[176:177], v[176:177]
	v_pk_mul_f32 v[196:197], v[192:193], v[192:193]
	v_mov_b32_e32 v198, v141
	v_mov_b32_e32 v199, v137
	v_pk_fma_f32 v[98:99], v[106:107], v[106:107], v[98:99]
	v_lshlrev_b32_e32 v156, 16, v105
	v_and_b32_e32 v157, 0xffff0000, v105
	v_lshlrev_b32_e32 v188, 16, v89
	v_and_b32_e32 v189, 0xffff0000, v89
	v_pk_fma_f32 v[98:99], v[198:199], v[198:199], v[98:99]
	v_mov_b32_e32 v106, v196
	v_mov_b32_e32 v107, v178
	v_pk_mul_f32 v[158:159], v[156:157], v[156:157]
	v_pk_mul_f32 v[190:191], v[188:189], v[188:189]
	v_pk_add_f32 v[98:99], v[106:107], v[98:99]
	v_mov_b32_e32 v178, v197
	v_pk_add_f32 v[98:99], v[178:179], v[98:99]
	v_mov_b32_e32 v106, v190
	v_mov_b32_e32 v107, v158
	v_pk_add_f32 v[98:99], v[106:107], v[98:99]
	v_mov_b32_e32 v158, v191
	v_pk_add_f32 v[98:99], v[158:159], v[98:99]
	v_mov_b32_e32 v107, v99
	v_mov_b32_e32 v106, v98
	s_nop 1
	v_permlane32_swap_b32 v99, v107
	v_permlane32_swap_b32 v98, v106
	global_store_dwordx2 v[100:101], v[92:93], off offset:512
	global_store_dwordx2 v[102:103], v[94:95], off offset:512
	global_store_dwordx2 v[100:101], v[84:85], off offset:1024
	global_store_dwordx2 v[102:103], v[86:87], off offset:1024
	global_store_dwordx2 v[100:101], v[104:105], off offset:1536
	global_store_dwordx2 v[102:103], v[88:89], off offset:1536
	v_pk_add_f32 v[88:89], v[32:33], 1.0 op_sel_hi:[1,0]
	v_pk_add_f32 v[92:93], v[34:35], 1.0 op_sel_hi:[1,0]
	s_waitcnt lgkmcnt(0)
	v_pk_add_f32 v[84:85], v[98:99], v[106:107]
	v_mov_b32_e32 v87, v85
	v_mov_b32_e32 v86, v84
	s_nop 1
	v_permlane16_swap_b32 v85, v87
	v_permlane16_swap_b32 v84, v86
	v_pk_add_f32 v[94:95], v[44:45], 1.0 op_sel_hi:[1,0]
	v_pk_add_f32 v[98:99], v[46:47], 1.0 op_sel_hi:[1,0]
	v_lshl_add_u64 v[100:101], s[62:63], 0, v[124:125]
	v_lshlrev_b32_e32 v102, 1, v160
	s_waitcnt lgkmcnt(0)
	v_pk_add_f32 v[84:85], v[84:85], v[86:87]
	s_nop 1
	v_mov_b32_dpp v87, v85 row_ror:8 row_mask:0xf bank_mask:0xf
	v_mov_b32_dpp v86, v84 row_ror:8 row_mask:0xf bank_mask:0xf
	v_mov_b32_e32 v103, v145
	v_lshl_add_u64 v[104:105], v[100:101], 0, v[102:103]
	v_lshl_add_u64 v[106:107], s[62:63], 0, v[126:127]
	v_pk_add_f32 v[124:125], v[60:61], 1.0 op_sel_hi:[1,0]
	s_waitcnt lgkmcnt(0)
	v_pk_add_f32 v[84:85], v[84:85], v[86:87]
	s_nop 1
	v_mov_b32_dpp v87, v85 row_shl:4 row_mask:0xf bank_mask:0x5
	v_mov_b32_dpp v86, v84 row_shl:4 row_mask:0xf bank_mask:0x5
	v_mov_b32_dpp v87, v85 row_shr:4 row_mask:0xf bank_mask:0xa
	v_mov_b32_dpp v86, v84 row_shr:4 row_mask:0xf bank_mask:0xa
	v_pk_add_f32 v[126:127], v[62:63], 1.0 op_sel_hi:[1,0]
	v_lshlrev_b32_e32 v158, 1, v161
	v_mov_b32_e32 v159, v145
	v_lshl_add_u64 v[178:179], v[100:101], 0, v[158:159]
	s_waitcnt lgkmcnt(0)
	v_pk_add_f32 v[84:85], v[84:85], v[86:87]
	s_nop 1
	v_mov_b32_dpp v87, v85 quad_perm:[2,3,0,1] row_mask:0xf bank_mask:0xf
	v_mov_b32_dpp v86, v84 quad_perm:[2,3,0,1] row_mask:0xf bank_mask:0xf
	v_pk_add_f32 v[190:191], v[72:73], 1.0 op_sel_hi:[1,0]
	v_pk_add_f32 v[196:197], v[74:75], 1.0 op_sel_hi:[1,0]
	v_lshl_add_u64 v[102:103], v[106:107], 0, v[102:103]
	v_lshl_add_u64 v[158:159], v[106:107], 0, v[158:159]
	s_waitcnt lgkmcnt(0)
	v_pk_add_f32 v[84:85], v[84:85], v[86:87]
	s_nop 1
	v_mov_b32_dpp v87, v85 quad_perm:[1,0,3,2] row_mask:0xf bank_mask:0xf
	v_mov_b32_dpp v86, v84 quad_perm:[1,0,3,2] row_mask:0xf bank_mask:0xf
	s_waitcnt lgkmcnt(0)
	v_pk_add_f32 v[84:85], v[84:85], v[86:87]
	s_nop 0
	v_pk_fma_f32 v[84:85], v[84:85], s[24:25], v[130:131] op_sel_hi:[1,0,0]
	v_mov_b32_e32 v87, v145
	v_mul_f32_e32 v86, 0x4b800000, v85
	v_cmp_gt_f32_e32 vcc, s5, v85
	s_nop 1
	v_cndmask_b32_e32 v85, v85, v86, vcc
	v_rsq_f32_e32 v85, v85
	v_lshlrev_b32_e32 v86, 1, v162
	v_lshl_add_u64 v[100:101], v[100:101], 0, v[86:87]
	v_mul_f32_e32 v130, 0x45800000, v85
	v_cndmask_b32_e32 v130, v85, v130, vcc
	v_pk_mul_f32 v[96:97], v[130:131], v[96:97] op_sel_hi:[0,1]
	v_pk_mul_f32 v[90:91], v[130:131], v[90:91] op_sel_hi:[0,1]
	v_pk_mul_f32 v[96:97], v[20:21], v[96:97]
	v_pk_mul_f32 v[90:91], v[22:23], v[90:91]
	v_pk_fma_f32 v[96:97], v[88:89], v[96:97], v[36:37]
	v_pk_fma_f32 v[90:91], v[92:93], v[90:91], v[38:39]
	v_cvt_pk_bf16_f32 v96, v96, v97
	v_cvt_pk_bf16_f32 v97, v90, v91
	global_store_dwordx2 v[122:123], v[96:97], off
	v_pk_mul_f32 v[90:91], v[130:131], v[110:111] op_sel_hi:[0,1]
	v_pk_mul_f32 v[96:97], v[130:131], v[108:109] op_sel_hi:[0,1]
	v_pk_mul_f32 v[90:91], v[16:17], v[90:91]
	v_pk_mul_f32 v[96:97], v[18:19], v[96:97]
	v_pk_fma_f32 v[90:91], v[94:95], v[90:91], v[48:49]
	v_pk_fma_f32 v[96:97], v[98:99], v[96:97], v[50:51]
	v_cvt_pk_bf16_f32 v90, v90, v91
	v_cvt_pk_bf16_f32 v91, v96, v97
	global_store_dwordx2 v[104:105], v[90:91], off
	v_pk_mul_f32 v[90:91], v[130:131], v[138:139] op_sel_hi:[0,1]
	v_pk_mul_f32 v[96:97], v[130:131], v[136:137] op_sel_hi:[0,1]
	v_pk_mul_f32 v[90:91], v[4:5], v[90:91]
	v_pk_mul_f32 v[96:97], v[6:7], v[96:97]
	v_pk_fma_f32 v[90:91], v[124:125], v[90:91], v[56:57]
	v_pk_fma_f32 v[96:97], v[126:127], v[96:97], v[58:59]
	v_mul_f32_e32 v85, 0x4b800000, v84
	v_cmp_gt_f32_e32 vcc, s5, v84
	v_cvt_pk_bf16_f32 v90, v90, v91
	v_cvt_pk_bf16_f32 v91, v96, v97
	v_cndmask_b32_e32 v84, v84, v85, vcc
	global_store_dwordx2 v[178:179], v[90:91], off
	v_pk_mul_f32 v[90:91], v[130:131], v[176:177] op_sel_hi:[0,1]
	v_pk_mul_f32 v[96:97], v[130:131], v[156:157] op_sel_hi:[0,1]
	v_rsq_f32_e32 v104, v84
	v_pk_mul_f32 v[90:91], v[0:1], v[90:91]
	v_pk_mul_f32 v[96:97], v[2:3], v[96:97]
	v_pk_fma_f32 v[90:91], v[190:191], v[90:91], v[76:77]
	v_pk_fma_f32 v[96:97], v[196:197], v[96:97], v[78:79]
	v_cvt_pk_bf16_f32 v84, v90, v91
	v_cvt_pk_bf16_f32 v85, v96, v97
	global_store_dwordx2 v[100:101], v[84:85], off
	v_mul_f32_e32 v84, 0x45800000, v104
	v_cndmask_b32_e32 v84, v104, v84, vcc
	v_pk_mul_f32 v[82:83], v[84:85], v[82:83] op_sel_hi:[0,1]
	v_pk_mul_f32 v[80:81], v[84:85], v[80:81] op_sel_hi:[0,1]
	v_pk_mul_f32 v[82:83], v[20:21], v[82:83]
	v_pk_mul_f32 v[80:81], v[22:23], v[80:81]
	v_pk_fma_f32 v[82:83], v[88:89], v[82:83], v[36:37]
	v_pk_fma_f32 v[80:81], v[92:93], v[80:81], v[38:39]
	v_cvt_pk_bf16_f32 v82, v82, v83
	v_cvt_pk_bf16_f32 v83, v80, v81
	v_pk_mul_f32 v[80:81], v[84:85], v[134:135] op_sel_hi:[0,1]
	v_pk_mul_f32 v[88:89], v[84:85], v[132:133] op_sel_hi:[0,1]
	v_pk_mul_f32 v[80:81], v[16:17], v[80:81]
	v_pk_mul_f32 v[88:89], v[18:19], v[88:89]
	v_pk_fma_f32 v[80:81], v[94:95], v[80:81], v[48:49]
	v_pk_fma_f32 v[88:89], v[98:99], v[88:89], v[50:51]
	v_cvt_pk_bf16_f32 v80, v80, v81
	v_cvt_pk_bf16_f32 v81, v88, v89
	v_pk_mul_f32 v[88:89], v[84:85], v[142:143] op_sel_hi:[0,1]
	v_pk_mul_f32 v[90:91], v[84:85], v[140:141] op_sel_hi:[0,1]
	v_pk_mul_f32 v[88:89], v[4:5], v[88:89]
	v_pk_mul_f32 v[90:91], v[6:7], v[90:91]
	v_pk_fma_f32 v[88:89], v[124:125], v[88:89], v[56:57]
	v_pk_fma_f32 v[90:91], v[126:127], v[90:91], v[58:59]
	v_cvt_pk_bf16_f32 v88, v88, v89
	v_cvt_pk_bf16_f32 v89, v90, v91
	global_store_dwordx2 v[120:121], v[82:83], off
	global_store_dwordx2 v[102:103], v[80:81], off
	global_store_dwordx2 v[158:159], v[88:89], off
	v_pk_mul_f32 v[80:81], v[84:85], v[192:193] op_sel_hi:[0,1]
	v_pk_mul_f32 v[82:83], v[84:85], v[188:189] op_sel_hi:[0,1]
	v_pk_mul_f32 v[80:81], v[0:1], v[80:81]
	v_pk_mul_f32 v[82:83], v[2:3], v[82:83]
	v_pk_fma_f32 v[80:81], v[190:191], v[80:81], v[76:77]
	v_pk_fma_f32 v[82:83], v[196:197], v[82:83], v[78:79]
	v_cmp_ge_i32_e32 vcc, v118, v186
	v_cvt_pk_bf16_f32 v80, v80, v81
	v_cvt_pk_bf16_f32 v81, v82, v83
	v_lshl_add_u64 v[82:83], v[106:107], 0, v[86:87]
	s_or_b64 s[16:17], vcc, s[16:17]
	global_store_dwordx2 v[82:83], v[80:81], off
	s_andn2_b64 exec, exec, s[16:17]
	s_cbranch_execz .LBB0_330

.LBB0_1021:
	s_or_b64 exec, exec, s[0:1]
	s_waitcnt vmcnt(11)
	v_and_b32_e32 v133, 0xffff0000, v118
	s_waitcnt vmcnt(3)
	v_and_b32_e32 v141, 0xffff0000, v108
	v_lshlrev_b32_e32 v132, 16, v118
	v_lshlrev_b32_e32 v140, 16, v108
	v_mov_b32_e32 v178, v141
	v_mov_b32_e32 v179, v133
	v_lshlrev_b32_e32 v134, 16, v119
	v_lshlrev_b32_e32 v108, 16, v109
	v_mov_b32_e32 v176, v140
	v_mov_b32_e32 v177, v132
	v_pk_mul_f32 v[178:179], v[178:179], v[178:179]
	v_and_b32_e32 v135, 0xffff0000, v119
	v_and_b32_e32 v109, 0xffff0000, v109
	v_pk_fma_f32 v[176:177], v[176:177], v[176:177], v[178:179]
	v_mov_b32_e32 v178, v108
	v_mov_b32_e32 v179, v134
	v_lshlrev_b32_e32 v136, 16, v116
	s_waitcnt vmcnt(2)
	v_lshlrev_b32_e32 v142, 16, v106
	v_pk_fma_f32 v[176:177], v[178:179], v[178:179], v[176:177]
	v_mov_b32_e32 v178, v109
	v_mov_b32_e32 v179, v135
	v_and_b32_e32 v137, 0xffff0000, v116
	v_and_b32_e32 v143, 0xffff0000, v106
	v_pk_fma_f32 v[176:177], v[178:179], v[178:179], v[176:177]
	v_mov_b32_e32 v178, v142
	v_mov_b32_e32 v179, v136
	v_lshlrev_b32_e32 v138, 16, v117
	v_lshlrev_b32_e32 v106, 16, v107
	v_pk_fma_f32 v[176:177], v[178:179], v[178:179], v[176:177]
	v_mov_b32_e32 v178, v143
	v_mov_b32_e32 v179, v137
	v_and_b32_e32 v139, 0xffff0000, v117
	v_and_b32_e32 v107, 0xffff0000, v107
	v_pk_fma_f32 v[176:177], v[178:179], v[178:179], v[176:177]
	v_mov_b32_e32 v178, v106
	v_mov_b32_e32 v179, v138
	v_lshlrev_b32_e32 v118, 16, v112
	s_waitcnt vmcnt(1)
	v_lshlrev_b32_e32 v168, 16, v104
	v_pk_fma_f32 v[176:177], v[178:179], v[178:179], v[176:177]
	v_mov_b32_e32 v178, v107
	v_mov_b32_e32 v179, v139
	v_and_b32_e32 v119, 0xffff0000, v112
	v_and_b32_e32 v169, 0xffff0000, v104
	v_pk_fma_f32 v[176:177], v[178:179], v[178:179], v[176:177]
	v_mov_b32_e32 v178, v168
	v_mov_b32_e32 v179, v118
	v_lshlrev_b32_e32 v116, 16, v113
	v_lshlrev_b32_e32 v104, 16, v105
	v_pk_fma_f32 v[176:177], v[178:179], v[178:179], v[176:177]
	v_mov_b32_e32 v178, v169
	v_mov_b32_e32 v179, v119
	v_and_b32_e32 v117, 0xffff0000, v113
	v_lshlrev_b32_e32 v112, 16, v110
	v_and_b32_e32 v113, 0xffff0000, v110
	v_and_b32_e32 v105, 0xffff0000, v105
	s_waitcnt vmcnt(0)
	v_lshlrev_b32_e32 v170, 16, v102
	v_and_b32_e32 v171, 0xffff0000, v102
	v_pk_fma_f32 v[176:177], v[178:179], v[178:179], v[176:177]
	v_mov_b32_e32 v178, v104
	v_mov_b32_e32 v179, v116
	v_pk_mul_f32 v[172:173], v[112:113], v[112:113]
	v_pk_mul_f32 v[194:195], v[170:171], v[170:171]
	v_pk_fma_f32 v[176:177], v[178:179], v[178:179], v[176:177]
	v_mov_b32_e32 v178, v105
	v_mov_b32_e32 v179, v117
	v_lshlrev_b32_e32 v110, 16, v111
	v_and_b32_e32 v111, 0xffff0000, v111
	v_lshlrev_b32_e32 v102, 16, v103
	v_and_b32_e32 v103, 0xffff0000, v103
	v_pk_fma_f32 v[176:177], v[178:179], v[178:179], v[176:177]
	v_mov_b32_e32 v178, v194
	v_mov_b32_e32 v179, v172
	v_pk_mul_f32 v[174:175], v[110:111], v[110:111]
	v_pk_add_f32 v[176:177], v[178:179], v[176:177]
	v_pk_mul_f32 v[178:179], v[102:103], v[102:103]
	v_mov_b32_e32 v172, v195
	v_pk_add_f32 v[172:173], v[172:173], v[176:177]
	v_mov_b32_e32 v176, v178
	v_mov_b32_e32 v177, v174
	v_pk_add_f32 v[172:173], v[176:177], v[172:173]
	v_mov_b32_e32 v174, v179
	v_pk_add_f32 v[172:173], v[174:175], v[172:173]
	v_mov_b32_e32 v175, v173
	v_mov_b32_e32 v174, v172
	s_nop 1
	v_permlane32_swap_b32 v173, v175
	v_permlane32_swap_b32 v172, v174
	v_lshlrev_b32_e32 v196, 16, v92
	v_and_b32_e32 v197, 0xffff0000, v92
	v_lshlrev_b32_e32 v198, 16, v93
	v_and_b32_e32 v199, 0xffff0000, v93
	s_waitcnt lgkmcnt(0)
	v_pk_add_f32 v[172:173], v[172:173], v[174:175]
	v_mov_b32_e32 v175, v173
	v_mov_b32_e32 v174, v172
	s_nop 1
	v_permlane16_swap_b32 v173, v175
	v_permlane16_swap_b32 v172, v174
	v_lshlrev_b32_e32 v200, 16, v90
	v_and_b32_e32 v201, 0xffff0000, v90
	v_lshlrev_b32_e32 v202, 16, v91
	v_and_b32_e32 v203, 0xffff0000, v91
	s_waitcnt lgkmcnt(0)
	v_pk_add_f32 v[172:173], v[172:173], v[174:175]
	s_nop 1
	v_mov_b32_dpp v175, v173 row_ror:8 row_mask:0xf bank_mask:0xf
	v_mov_b32_dpp v174, v172 row_ror:8 row_mask:0xf bank_mask:0xf
	v_mov_b64_e32 v[90:91], s[50:51]
	v_lshlrev_b32_e32 v204, 16, v89
	v_and_b32_e32 v205, 0xffff0000, v89
	v_lshlrev_b32_e32 v122, 16, v114
	s_waitcnt lgkmcnt(0)
	v_pk_add_f32 v[172:173], v[172:173], v[174:175]
	s_nop 1
	v_mov_b32_dpp v175, v173 row_shl:4 row_mask:0xf bank_mask:0x5
	v_mov_b32_dpp v174, v172 row_shl:4 row_mask:0xf bank_mask:0x5
	v_mov_b32_dpp v175, v173 row_shr:4 row_mask:0xf bank_mask:0xa
	v_mov_b32_dpp v174, v172 row_shr:4 row_mask:0xf bank_mask:0xa
	v_and_b32_e32 v123, 0xffff0000, v114
	v_lshlrev_b32_e32 v120, 16, v115
	v_and_b32_e32 v121, 0xffff0000, v115
	v_lshlrev_b32_e32 v194, 16, v96
	s_waitcnt lgkmcnt(0)
	v_pk_add_f32 v[172:173], v[172:173], v[174:175]
	s_nop 1
	v_mov_b32_dpp v175, v173 quad_perm:[2,3,0,1] row_mask:0xf bank_mask:0xf
	v_mov_b32_dpp v174, v172 quad_perm:[2,3,0,1] row_mask:0xf bank_mask:0xf
	v_and_b32_e32 v195, 0xffff0000, v96
	v_lshlrev_b32_e32 v96, 16, v97
	v_and_b32_e32 v97, 0xffff0000, v97
	v_lshlrev_b32_e32 v114, 16, v100
	s_waitcnt lgkmcnt(0)
	v_pk_add_f32 v[92:93], v[172:173], v[174:175]
	s_nop 1
	v_mov_b32_dpp v173, v93 quad_perm:[1,0,3,2] row_mask:0xf bank_mask:0xf
	v_mov_b32_dpp v172, v92 quad_perm:[1,0,3,2] row_mask:0xf bank_mask:0xf
	v_lshlrev_b32_e32 v174, 16, v88
	v_and_b32_e32 v175, 0xffff0000, v88
	v_and_b32_e32 v115, 0xffff0000, v100
	v_lshlrev_b32_e32 v100, 16, v101
	s_waitcnt lgkmcnt(0)
	v_pk_add_f32 v[92:93], v[92:93], v[172:173]
	v_and_b32_e32 v101, 0xffff0000, v101
	v_pk_fma_f32 v[92:93], v[92:93], s[48:49], v[90:91] op_sel_hi:[1,0,0]
	v_lshlrev_b32_e32 v176, 16, v98
	v_mul_f32_e32 v88, 0x4b800000, v93
	v_cmp_gt_f32_e32 vcc, s5, v93
	v_cmp_gt_f32_e64 s[0:1], s5, v92
	v_and_b32_e32 v177, 0xffff0000, v98
	v_cndmask_b32_e32 v88, v93, v88, vcc
	v_mul_f32_e32 v93, 0x4b800000, v92
	v_rsq_f32_e32 v88, v88
	v_cndmask_b32_e64 v92, v92, v93, s[0:1]
	v_rsq_f32_e32 v92, v92
	v_lshlrev_b32_e32 v98, 16, v99
	v_mul_f32_e32 v89, 0x45800000, v88
	v_cndmask_b32_e32 v164, v88, v89, vcc
	v_mul_f32_e32 v88, 0x45800000, v92
	v_cndmask_b32_e64 v166, v92, v88, s[0:1]
	v_pk_mul_f32 v[88:89], v[164:165], v[132:133] op_sel_hi:[0,1]
	v_pk_mul_f32 v[92:93], v[164:165], v[134:135] op_sel_hi:[0,1]
	v_pk_mul_f32 v[88:89], v[28:29], v[88:89]
	v_pk_mul_f32 v[92:93], v[30:31], v[92:93]
	v_pk_fma_f32 v[88:89], v[40:41], v[88:89], v[122:123]
	v_pk_fma_f32 v[92:93], v[42:43], v[92:93], v[120:121]
	v_cvt_pk_bf16_f32 v88, v88, v89
	v_cvt_pk_bf16_f32 v89, v92, v93
	v_pk_mul_f32 v[92:93], v[166:167], v[140:141] op_sel_hi:[0,1]
	v_pk_mul_f32 v[108:109], v[166:167], v[108:109] op_sel_hi:[0,1]
	v_pk_mul_f32 v[92:93], v[28:29], v[92:93]
	v_pk_mul_f32 v[108:109], v[30:31], v[108:109]
	v_pk_fma_f32 v[92:93], v[40:41], v[92:93], v[194:195]
	v_pk_fma_f32 v[96:97], v[42:43], v[108:109], v[96:97]
	v_cvt_pk_bf16_f32 v92, v92, v93
	v_cvt_pk_bf16_f32 v93, v96, v97
	v_pk_mul_f32 v[96:97], v[164:165], v[136:137] op_sel_hi:[0,1]
	v_pk_mul_f32 v[108:109], v[164:165], v[138:139] op_sel_hi:[0,1]
	v_pk_mul_f32 v[96:97], v[20:21], v[96:97]
	v_pk_mul_f32 v[108:109], v[22:23], v[108:109]
	v_pk_fma_f32 v[96:97], v[52:53], v[96:97], v[114:115]
	v_pk_fma_f32 v[100:101], v[54:55], v[108:109], v[100:101]
	v_cvt_pk_bf16_f32 v96, v96, v97
	v_cvt_pk_bf16_f32 v97, v100, v101
	v_pk_mul_f32 v[100:101], v[166:167], v[142:143] op_sel_hi:[0,1]
	v_pk_mul_f32 v[106:107], v[166:167], v[106:107] op_sel_hi:[0,1]
	v_pk_mul_f32 v[100:101], v[20:21], v[100:101]
	v_pk_mul_f32 v[106:107], v[22:23], v[106:107]
	v_pk_fma_f32 v[100:101], v[52:53], v[100:101], v[196:197]
	v_pk_fma_f32 v[106:107], v[54:55], v[106:107], v[198:199]
	v_cvt_pk_bf16_f32 v100, v100, v101
	v_cvt_pk_bf16_f32 v101, v106, v107
	v_pk_mul_f32 v[106:107], v[164:165], v[118:119] op_sel_hi:[0,1]
	v_pk_mul_f32 v[108:109], v[164:165], v[116:117] op_sel_hi:[0,1]
	v_and_b32_e32 v99, 0xffff0000, v99
	v_pk_mul_f32 v[106:107], v[12:13], v[106:107]
	v_pk_mul_f32 v[108:109], v[14:15], v[108:109]
	v_pk_fma_f32 v[106:107], v[64:65], v[106:107], v[176:177]
	v_pk_fma_f32 v[98:99], v[66:67], v[108:109], v[98:99]
	v_cvt_pk_bf16_f32 v106, v106, v107
	v_cvt_pk_bf16_f32 v107, v98, v99
	v_pk_mul_f32 v[98:99], v[166:167], v[168:169] op_sel_hi:[0,1]
	v_pk_mul_f32 v[104:105], v[166:167], v[104:105] op_sel_hi:[0,1]
	v_pk_mul_f32 v[98:99], v[12:13], v[98:99]
	v_pk_mul_f32 v[104:105], v[14:15], v[104:105]
	v_pk_fma_f32 v[98:99], v[64:65], v[98:99], v[200:201]
	v_pk_fma_f32 v[104:105], v[66:67], v[104:105], v[202:203]
	v_cvt_pk_bf16_f32 v98, v98, v99
	v_cvt_pk_bf16_f32 v99, v104, v105
	v_pk_mul_f32 v[104:105], v[164:165], v[112:113] op_sel_hi:[0,1]
	v_pk_mul_f32 v[108:109], v[164:165], v[110:111] op_sel_hi:[0,1]
	v_lshlrev_b32_e32 v178, 16, v94
	v_and_b32_e32 v179, 0xffff0000, v94
	v_lshlrev_b32_e32 v94, 16, v95
	v_and_b32_e32 v95, 0xffff0000, v95
	v_pk_mul_f32 v[104:105], v[4:5], v[104:105]
	v_pk_mul_f32 v[108:109], v[6:7], v[108:109]
	v_pk_fma_f32 v[104:105], v[68:69], v[104:105], v[178:179]
	v_pk_fma_f32 v[94:95], v[70:71], v[108:109], v[94:95]
	v_cvt_pk_bf16_f32 v104, v104, v105
	v_cvt_pk_bf16_f32 v105, v94, v95
	v_pk_mul_f32 v[94:95], v[166:167], v[170:171] op_sel_hi:[0,1]
	v_pk_mul_f32 v[102:103], v[166:167], v[102:103] op_sel_hi:[0,1]
	v_pk_mul_f32 v[94:95], v[4:5], v[94:95]
	v_pk_mul_f32 v[102:103], v[6:7], v[102:103]
	v_and_b32_e32 v109, 0xffff0000, v88
	v_and_b32_e32 v115, 0xffff0000, v92
	v_pk_fma_f32 v[94:95], v[68:69], v[94:95], v[174:175]
	v_pk_fma_f32 v[102:103], v[70:71], v[102:103], v[204:205]
	v_lshlrev_b32_e32 v108, 16, v88
	v_lshlrev_b32_e32 v114, 16, v92
	v_mov_b32_e32 v118, v115
	v_mov_b32_e32 v119, v109
	v_cvt_pk_bf16_f32 v94, v94, v95
	v_cvt_pk_bf16_f32 v95, v102, v103
	v_lshlrev_b32_e32 v102, 16, v89
	v_lshlrev_b32_e32 v110, 16, v93
	v_mov_b32_e32 v116, v114
	v_mov_b32_e32 v117, v108
	v_pk_mul_f32 v[118:119], v[118:119], v[118:119]
	v_and_b32_e32 v103, 0xffff0000, v89
	v_and_b32_e32 v111, 0xffff0000, v93
	v_mov_b32_e32 v112, v110
	v_mov_b32_e32 v113, v102
	v_pk_fma_f32 v[116:117], v[116:117], v[116:117], v[118:119]
	v_lshlrev_b32_e32 v120, 16, v96
	v_lshlrev_b32_e32 v132, 16, v100
	v_mov_b32_e32 v196, v111
	v_mov_b32_e32 v197, v103
	v_pk_fma_f32 v[112:113], v[112:113], v[112:113], v[116:117]
	v_and_b32_e32 v121, 0xffff0000, v96
	v_and_b32_e32 v133, 0xffff0000, v100
	v_pk_fma_f32 v[112:113], v[196:197], v[196:197], v[112:113]
	v_mov_b32_e32 v198, v132
	v_mov_b32_e32 v199, v120
	v_lshlrev_b32_e32 v118, 16, v97
	v_lshlrev_b32_e32 v122, 16, v101
	v_mov_b32_e32 v200, v133
	v_mov_b32_e32 v201, v121
	v_pk_fma_f32 v[112:113], v[198:199], v[198:199], v[112:113]
	v_and_b32_e32 v119, 0xffff0000, v97
	v_and_b32_e32 v123, 0xffff0000, v101
	v_mov_b32_e32 v116, v122
	v_mov_b32_e32 v117, v118
	v_pk_fma_f32 v[112:113], v[200:201], v[200:201], v[112:113]
	v_lshlrev_b32_e32 v136, 16, v106
	v_lshlrev_b32_e32 v140, 16, v98
	v_mov_b32_e32 v196, v123
	v_mov_b32_e32 v197, v119
	v_pk_fma_f32 v[112:113], v[116:117], v[116:117], v[112:113]
	v_and_b32_e32 v137, 0xffff0000, v106
	v_and_b32_e32 v141, 0xffff0000, v98
	v_pk_fma_f32 v[112:113], v[196:197], v[196:197], v[112:113]
	v_mov_b32_e32 v198, v140
	v_mov_b32_e32 v199, v136
	v_lshlrev_b32_e32 v134, 16, v107
	v_lshlrev_b32_e32 v138, 16, v99
	v_mov_b32_e32 v200, v141
	v_mov_b32_e32 v201, v137
	v_pk_fma_f32 v[112:113], v[198:199], v[198:199], v[112:113]
	v_and_b32_e32 v135, 0xffff0000, v107
	v_and_b32_e32 v139, 0xffff0000, v99
	v_lshlrev_b32_e32 v170, 16, v104
	v_and_b32_e32 v171, 0xffff0000, v104
	v_lshlrev_b32_e32 v178, 16, v94
	v_and_b32_e32 v179, 0xffff0000, v94
	v_mov_b32_e32 v116, v138
	v_mov_b32_e32 v117, v134
	v_pk_fma_f32 v[112:113], v[200:201], v[200:201], v[112:113]
	v_pk_mul_f32 v[172:173], v[170:171], v[170:171]
	v_pk_mul_f32 v[194:195], v[178:179], v[178:179]
	v_mov_b32_e32 v196, v139
	v_mov_b32_e32 v197, v135
	v_pk_fma_f32 v[112:113], v[116:117], v[116:117], v[112:113]
	v_lshlrev_b32_e32 v142, 16, v105
	v_and_b32_e32 v143, 0xffff0000, v105
	v_lshlrev_b32_e32 v174, 16, v95
	v_and_b32_e32 v175, 0xffff0000, v95
	v_pk_fma_f32 v[112:113], v[196:197], v[196:197], v[112:113]
	v_mov_b32_e32 v116, v194
	v_mov_b32_e32 v117, v172
	v_pk_mul_f32 v[168:169], v[142:143], v[142:143]
	v_pk_mul_f32 v[176:177], v[174:175], v[174:175]
	v_pk_add_f32 v[112:113], v[116:117], v[112:113]
	v_mov_b32_e32 v172, v195
	v_pk_add_f32 v[112:113], v[172:173], v[112:113]
	v_mov_b32_e32 v116, v176
	v_mov_b32_e32 v117, v168
	v_pk_add_f32 v[112:113], v[116:117], v[112:113]
	v_mov_b32_e32 v168, v177
	v_pk_add_f32 v[112:113], v[168:169], v[112:113]
	v_mov_b32_e32 v117, v113
	v_mov_b32_e32 v116, v112
	s_nop 1
	v_permlane32_swap_b32 v113, v117
	v_permlane32_swap_b32 v112, v116
	v_lshl_add_u64 v[168:169], v[86:87], 0, s[14:15]
	v_lshl_add_u64 v[172:173], v[86:87], 0, s[16:17]
	v_lshl_add_u64 v[176:177], v[86:87], 0, s[18:19]
	v_lshl_add_u64 v[194:195], v[86:87], 0, s[20:21]
	s_waitcnt lgkmcnt(0)
	v_pk_add_f32 v[112:113], v[112:113], v[116:117]
	v_mov_b32_e32 v117, v113
	v_mov_b32_e32 v116, v112
	s_nop 1
	v_permlane16_swap_b32 v113, v117
	v_permlane16_swap_b32 v112, v116
	v_lshl_add_u64 v[196:197], v[86:87], 0, s[22:23]
	v_lshl_add_u64 v[198:199], v[86:87], 0, s[24:25]
	v_lshl_add_u64 v[200:201], v[86:87], 0, s[38:39]
	v_lshl_add_u64 v[202:203], v[86:87], 0, s[40:41]
	s_waitcnt lgkmcnt(0)
	v_pk_add_f32 v[112:113], v[112:113], v[116:117]
	s_nop 1
	v_mov_b32_dpp v117, v113 row_ror:8 row_mask:0xf bank_mask:0xf
	v_mov_b32_dpp v116, v112 row_ror:8 row_mask:0xf bank_mask:0xf
	v_add_co_u32_e32 v86, vcc, s6, v86
	v_add_u32_e32 v131, 2, v131
	s_nop 0
	v_addc_co_u32_e32 v87, vcc, 0, v87, vcc
	global_store_dwordx2 v[86:87], v[88:89], off
	s_waitcnt lgkmcnt(0)
	v_pk_add_f32 v[88:89], v[112:113], v[116:117]
	s_nop 1
	v_mov_b32_dpp v113, v89 row_shl:4 row_mask:0xf bank_mask:0x5
	v_mov_b32_dpp v112, v88 row_shl:4 row_mask:0xf bank_mask:0x5
	v_mov_b32_dpp v113, v89 row_shr:4 row_mask:0xf bank_mask:0xa
	v_mov_b32_dpp v112, v88 row_shr:4 row_mask:0xf bank_mask:0xa
	global_store_dwordx2 v[86:87], v[92:93], off offset:2048
	global_store_dwordx2 v[86:87], v[96:97], off offset:512
	global_store_dwordx2 v[86:87], v[100:101], off offset:2560
	global_store_dwordx2 v[86:87], v[106:107], off offset:1024
	global_store_dwordx2 v[86:87], v[98:99], off offset:3072
	global_store_dwordx2 v[86:87], v[104:105], off offset:1536
	global_store_dwordx2 v[86:87], v[94:95], off offset:3584
	v_pk_add_f32 v[86:87], v[32:33], 1.0 op_sel_hi:[1,0]
	v_pk_add_f32 v[94:95], v[34:35], 1.0 op_sel_hi:[1,0]
	s_waitcnt lgkmcnt(0)
	v_pk_add_f32 v[88:89], v[88:89], v[112:113]
	s_nop 1
	v_mov_b32_dpp v93, v89 quad_perm:[2,3,0,1] row_mask:0xf bank_mask:0xf
	v_mov_b32_dpp v92, v88 quad_perm:[2,3,0,1] row_mask:0xf bank_mask:0xf
	v_pk_add_f32 v[96:97], v[44:45], 1.0 op_sel_hi:[1,0]
	v_pk_add_f32 v[98:99], v[46:47], 1.0 op_sel_hi:[1,0]
	v_pk_add_f32 v[100:101], v[60:61], 1.0 op_sel_hi:[1,0]
	v_pk_add_f32 v[104:105], v[74:75], 1.0 op_sel_hi:[1,0]
	s_waitcnt lgkmcnt(0)
	v_pk_add_f32 v[88:89], v[88:89], v[92:93]
	s_nop 1
	v_mov_b32_dpp v93, v89 quad_perm:[1,0,3,2] row_mask:0xf bank_mask:0xf
	v_mov_b32_dpp v92, v88 quad_perm:[1,0,3,2] row_mask:0xf bank_mask:0xf
	v_lshl_add_u64 v[82:83], v[82:83], 0, s[10:11]
	v_lshl_add_u64 v[84:85], v[84:85], 0, s[10:11]
	s_waitcnt lgkmcnt(0)
	v_pk_add_f32 v[88:89], v[88:89], v[92:93]
	s_nop 0
	v_pk_fma_f32 v[88:89], v[88:89], s[48:49], v[90:91] op_sel_hi:[1,0,0]
	v_pk_add_f32 v[92:93], v[72:73], 1.0 op_sel_hi:[1,0]
	v_mul_f32_e32 v90, 0x4b800000, v89
	v_cmp_gt_f32_e32 vcc, s5, v89
	s_nop 1
	v_cndmask_b32_e32 v89, v89, v90, vcc
	v_rsq_f32_e32 v89, v89
	v_pk_add_f32 v[90:91], v[62:63], 1.0 op_sel_hi:[1,0]
	v_mul_f32_e32 v106, 0x45800000, v89
	v_cndmask_b32_e32 v106, v89, v106, vcc
	v_pk_mul_f32 v[108:109], v[106:107], v[108:109] op_sel_hi:[0,1]
	v_pk_mul_f32 v[102:103], v[106:107], v[102:103] op_sel_hi:[0,1]
	v_pk_mul_f32 v[108:109], v[24:25], v[108:109]
	v_pk_mul_f32 v[102:103], v[26:27], v[102:103]
	v_pk_fma_f32 v[108:109], v[86:87], v[108:109], v[36:37]
	v_pk_fma_f32 v[102:103], v[94:95], v[102:103], v[38:39]
	v_cvt_pk_bf16_f32 v108, v108, v109
	v_cvt_pk_bf16_f32 v109, v102, v103
	global_store_dwordx2 v[168:169], v[108:109], off
	v_pk_mul_f32 v[102:103], v[106:107], v[120:121] op_sel_hi:[0,1]
	v_pk_mul_f32 v[108:109], v[106:107], v[118:119] op_sel_hi:[0,1]
	v_pk_mul_f32 v[102:103], v[16:17], v[102:103]
	v_pk_mul_f32 v[108:109], v[18:19], v[108:109]
	v_pk_fma_f32 v[102:103], v[96:97], v[102:103], v[48:49]
	v_pk_fma_f32 v[108:109], v[98:99], v[108:109], v[50:51]
	v_cvt_pk_bf16_f32 v102, v102, v103
	v_cvt_pk_bf16_f32 v103, v108, v109
	global_store_dwordx2 v[172:173], v[102:103], off
	v_pk_mul_f32 v[102:103], v[106:107], v[136:137] op_sel_hi:[0,1]
	v_pk_mul_f32 v[108:109], v[106:107], v[134:135] op_sel_hi:[0,1]
	v_pk_mul_f32 v[102:103], v[8:9], v[102:103]
	v_pk_mul_f32 v[108:109], v[10:11], v[108:109]
	v_pk_fma_f32 v[102:103], v[100:101], v[102:103], v[56:57]
	v_pk_fma_f32 v[108:109], v[90:91], v[108:109], v[58:59]
	v_mul_f32_e32 v89, 0x4b800000, v88
	v_cmp_gt_f32_e32 vcc, s5, v88
	v_cvt_pk_bf16_f32 v102, v102, v103
	v_cvt_pk_bf16_f32 v103, v108, v109
	v_cndmask_b32_e32 v88, v88, v89, vcc
	global_store_dwordx2 v[176:177], v[102:103], off
	v_pk_mul_f32 v[102:103], v[106:107], v[170:171] op_sel_hi:[0,1]
	v_pk_mul_f32 v[106:107], v[106:107], v[142:143] op_sel_hi:[0,1]
	v_rsq_f32_e32 v108, v88
	v_pk_mul_f32 v[102:103], v[0:1], v[102:103]
	v_pk_mul_f32 v[106:107], v[2:3], v[106:107]
	v_pk_fma_f32 v[102:103], v[92:93], v[102:103], v[76:77]
	v_pk_fma_f32 v[106:107], v[104:105], v[106:107], v[78:79]
	v_cvt_pk_bf16_f32 v88, v102, v103
	v_cvt_pk_bf16_f32 v89, v106, v107
	global_store_dwordx2 v[194:195], v[88:89], off
	v_mul_f32_e32 v88, 0x45800000, v108
	v_cndmask_b32_e32 v88, v108, v88, vcc
	v_pk_mul_f32 v[102:103], v[88:89], v[114:115] op_sel_hi:[0,1]
	v_pk_mul_f32 v[102:103], v[24:25], v[102:103]
	v_cmp_ge_i32_e32 vcc, v131, v186
	v_pk_fma_f32 v[86:87], v[86:87], v[102:103], v[36:37]
	v_pk_mul_f32 v[102:103], v[88:89], v[110:111] op_sel_hi:[0,1]
	v_pk_mul_f32 v[102:103], v[26:27], v[102:103]
	v_cvt_pk_bf16_f32 v86, v86, v87
	v_pk_fma_f32 v[94:95], v[94:95], v[102:103], v[38:39]
	s_or_b64 s[12:13], vcc, s[12:13]
	v_cvt_pk_bf16_f32 v87, v94, v95
	global_store_dwordx2 v[196:197], v[86:87], off
	v_pk_mul_f32 v[86:87], v[88:89], v[132:133] op_sel_hi:[0,1]
	v_pk_mul_f32 v[94:95], v[88:89], v[122:123] op_sel_hi:[0,1]
	v_pk_mul_f32 v[86:87], v[16:17], v[86:87]
	v_pk_mul_f32 v[94:95], v[18:19], v[94:95]
	v_pk_fma_f32 v[86:87], v[96:97], v[86:87], v[48:49]
	v_pk_fma_f32 v[94:95], v[98:99], v[94:95], v[50:51]
	v_cvt_pk_bf16_f32 v86, v86, v87
	v_cvt_pk_bf16_f32 v87, v94, v95
	global_store_dwordx2 v[198:199], v[86:87], off
	v_pk_mul_f32 v[86:87], v[88:89], v[140:141] op_sel_hi:[0,1]
	v_pk_mul_f32 v[94:95], v[88:89], v[138:139] op_sel_hi:[0,1]
	v_pk_mul_f32 v[86:87], v[8:9], v[86:87]
	v_pk_mul_f32 v[94:95], v[10:11], v[94:95]
	v_pk_fma_f32 v[86:87], v[100:101], v[86:87], v[56:57]
	v_pk_fma_f32 v[90:91], v[90:91], v[94:95], v[58:59]
	v_cvt_pk_bf16_f32 v86, v86, v87
	v_cvt_pk_bf16_f32 v87, v90, v91
	global_store_dwordx2 v[200:201], v[86:87], off
	v_pk_mul_f32 v[86:87], v[88:89], v[178:179] op_sel_hi:[0,1]
	v_pk_mul_f32 v[88:89], v[88:89], v[174:175] op_sel_hi:[0,1]
	v_pk_mul_f32 v[86:87], v[0:1], v[86:87]
	v_pk_mul_f32 v[88:89], v[2:3], v[88:89]
	v_pk_fma_f32 v[86:87], v[92:93], v[86:87], v[76:77]
	v_pk_fma_f32 v[88:89], v[104:105], v[88:89], v[78:79]
	v_cvt_pk_bf16_f32 v86, v86, v87
	v_cvt_pk_bf16_f32 v87, v88, v89
	global_store_dwordx2 v[202:203], v[86:87], off
	s_andn2_b64 exec, exec, s[12:13]
	s_cbranch_execz .LBB0_1024

.LBB0_1210:
	s_or_b64 exec, exec, s[0:1]
	s_waitcnt vmcnt(11)
	v_and_b32_e32 v81, 0xffff0000, v60
	s_waitcnt vmcnt(3)
	v_and_b32_e32 v89, 0xffff0000, v72
	v_lshlrev_b32_e32 v80, 16, v60
	v_lshlrev_b32_e32 v88, 16, v72
	v_mov_b32_e32 v102, v89
	v_mov_b32_e32 v103, v81
	v_lshlrev_b32_e32 v82, 16, v61
	v_lshlrev_b32_e32 v72, 16, v73
	v_mov_b32_e32 v100, v88
	v_mov_b32_e32 v101, v80
	v_pk_mul_f32 v[102:103], v[102:103], v[102:103]
	v_and_b32_e32 v83, 0xffff0000, v61
	v_and_b32_e32 v73, 0xffff0000, v73
	v_pk_fma_f32 v[100:101], v[100:101], v[100:101], v[102:103]
	v_mov_b32_e32 v102, v72
	v_mov_b32_e32 v103, v82
	v_lshlrev_b32_e32 v84, 16, v58
	s_waitcnt vmcnt(2)
	v_lshlrev_b32_e32 v90, 16, v70
	v_pk_fma_f32 v[100:101], v[102:103], v[102:103], v[100:101]
	v_mov_b32_e32 v102, v73
	v_mov_b32_e32 v103, v83
	v_and_b32_e32 v85, 0xffff0000, v58
	v_and_b32_e32 v91, 0xffff0000, v70
	v_pk_fma_f32 v[100:101], v[102:103], v[102:103], v[100:101]
	v_mov_b32_e32 v102, v90
	v_mov_b32_e32 v103, v84
	v_lshlrev_b32_e32 v86, 16, v59
	v_lshlrev_b32_e32 v70, 16, v71
	v_pk_fma_f32 v[100:101], v[102:103], v[102:103], v[100:101]
	v_mov_b32_e32 v102, v91
	v_mov_b32_e32 v103, v85
	v_and_b32_e32 v87, 0xffff0000, v59
	v_and_b32_e32 v71, 0xffff0000, v71
	v_pk_fma_f32 v[100:101], v[102:103], v[102:103], v[100:101]
	v_mov_b32_e32 v102, v70
	v_mov_b32_e32 v103, v86
	v_lshlrev_b32_e32 v60, 16, v54
	s_waitcnt vmcnt(1)
	v_lshlrev_b32_e32 v92, 16, v68
	v_pk_fma_f32 v[100:101], v[102:103], v[102:103], v[100:101]
	v_mov_b32_e32 v102, v71
	v_mov_b32_e32 v103, v87
	v_and_b32_e32 v61, 0xffff0000, v54
	v_and_b32_e32 v93, 0xffff0000, v68
	v_pk_fma_f32 v[100:101], v[102:103], v[102:103], v[100:101]
	v_mov_b32_e32 v102, v92
	v_mov_b32_e32 v103, v60
	v_lshlrev_b32_e32 v58, 16, v55
	v_lshlrev_b32_e32 v68, 16, v69
	v_pk_fma_f32 v[100:101], v[102:103], v[102:103], v[100:101]
	v_mov_b32_e32 v102, v93
	v_mov_b32_e32 v103, v61
	v_and_b32_e32 v59, 0xffff0000, v55
	v_lshlrev_b32_e32 v54, 16, v52
	v_and_b32_e32 v55, 0xffff0000, v52
	v_and_b32_e32 v69, 0xffff0000, v69
	s_waitcnt vmcnt(0)
	v_lshlrev_b32_e32 v94, 16, v66
	v_and_b32_e32 v95, 0xffff0000, v66
	v_pk_fma_f32 v[100:101], v[102:103], v[102:103], v[100:101]
	v_mov_b32_e32 v102, v68
	v_mov_b32_e32 v103, v58
	v_pk_mul_f32 v[96:97], v[54:55], v[54:55]
	v_pk_mul_f32 v[104:105], v[94:95], v[94:95]
	v_pk_fma_f32 v[100:101], v[102:103], v[102:103], v[100:101]
	v_mov_b32_e32 v102, v69
	v_mov_b32_e32 v103, v59
	v_lshlrev_b32_e32 v52, 16, v53
	v_and_b32_e32 v53, 0xffff0000, v53
	v_lshlrev_b32_e32 v66, 16, v67
	v_and_b32_e32 v67, 0xffff0000, v67
	v_pk_fma_f32 v[100:101], v[102:103], v[102:103], v[100:101]
	v_mov_b32_e32 v102, v104
	v_mov_b32_e32 v103, v96
	v_pk_mul_f32 v[98:99], v[52:53], v[52:53]
	v_pk_add_f32 v[100:101], v[102:103], v[100:101]
	v_pk_mul_f32 v[102:103], v[66:67], v[66:67]
	v_mov_b32_e32 v96, v105
	v_pk_add_f32 v[96:97], v[96:97], v[100:101]
	v_mov_b32_e32 v100, v102
	v_mov_b32_e32 v101, v98
	v_pk_add_f32 v[96:97], v[100:101], v[96:97]
	v_mov_b32_e32 v98, v103
	v_pk_add_f32 v[96:97], v[98:99], v[96:97]
	v_mov_b32_e32 v99, v97
	v_mov_b32_e32 v98, v96
	s_nop 1
	v_permlane32_swap_b32 v97, v99
	v_permlane32_swap_b32 v96, v98
	v_lshlrev_b32_e32 v108, 16, v40
	v_and_b32_e32 v109, 0xffff0000, v40
	v_lshlrev_b32_e32 v110, 16, v41
	v_and_b32_e32 v111, 0xffff0000, v41
	s_waitcnt lgkmcnt(0)
	v_pk_add_f32 v[96:97], v[96:97], v[98:99]
	v_mov_b32_e32 v99, v97
	v_mov_b32_e32 v98, v96
	s_nop 1
	v_permlane16_swap_b32 v97, v99
	v_permlane16_swap_b32 v96, v98
	v_lshlrev_b32_e32 v112, 16, v38
	v_and_b32_e32 v113, 0xffff0000, v38
	v_lshlrev_b32_e32 v114, 16, v39
	v_and_b32_e32 v115, 0xffff0000, v39
	s_waitcnt lgkmcnt(0)
	v_pk_add_f32 v[96:97], v[96:97], v[98:99]
	s_nop 1
	v_mov_b32_dpp v99, v97 row_ror:8 row_mask:0xf bank_mask:0xf
	v_mov_b32_dpp v98, v96 row_ror:8 row_mask:0xf bank_mask:0xf
	v_lshlrev_b32_e32 v64, 16, v56
	v_and_b32_e32 v65, 0xffff0000, v56
	v_pk_mul_f32 v[116:117], v[16:17], 0.5 op_sel_hi:[1,0]
	v_lshlrev_b32_e32 v62, 16, v57
	s_waitcnt lgkmcnt(0)
	v_pk_add_f32 v[96:97], v[96:97], v[98:99]
	s_nop 1
	v_mov_b32_dpp v99, v97 row_shl:4 row_mask:0xf bank_mask:0x5
	v_mov_b32_dpp v98, v96 row_shl:4 row_mask:0xf bank_mask:0x5
	v_mov_b32_dpp v99, v97 row_shr:4 row_mask:0xf bank_mask:0xa
	v_mov_b32_dpp v98, v96 row_shr:4 row_mask:0xf bank_mask:0xa
	v_and_b32_e32 v63, 0xffff0000, v57
	v_lshlrev_b32_e32 v104, 16, v46
	v_and_b32_e32 v105, 0xffff0000, v46
	v_lshlrev_b32_e32 v46, 16, v47
	s_waitcnt lgkmcnt(0)
	v_pk_add_f32 v[96:97], v[96:97], v[98:99]
	s_nop 1
	v_mov_b32_dpp v99, v97 quad_perm:[2,3,0,1] row_mask:0xf bank_mask:0xf
	v_mov_b32_dpp v98, v96 quad_perm:[2,3,0,1] row_mask:0xf bank_mask:0xf
	v_and_b32_e32 v47, 0xffff0000, v47
	v_lshlrev_b32_e32 v56, 16, v50
	v_and_b32_e32 v57, 0xffff0000, v50
	v_lshlrev_b32_e32 v50, 16, v51
	s_waitcnt lgkmcnt(0)
	v_pk_add_f32 v[96:97], v[96:97], v[98:99]
	s_nop 1
	v_mov_b32_dpp v99, v97 quad_perm:[1,0,3,2] row_mask:0xf bank_mask:0xf
	v_mov_b32_dpp v98, v96 quad_perm:[1,0,3,2] row_mask:0xf bank_mask:0xf
	v_and_b32_e32 v51, 0xffff0000, v51
	v_lshlrev_b32_e32 v106, 16, v42
	v_and_b32_e32 v107, 0xffff0000, v42
	v_lshlrev_b32_e32 v42, 16, v43
	s_waitcnt lgkmcnt(0)
	v_pk_add_f32 v[40:41], v[96:97], v[98:99]
	v_and_b32_e32 v43, 0xffff0000, v43
	v_pk_fma_f32 v[40:41], v[40:41], s[10:11], v[36:37] op_sel_hi:[1,0,0]
	v_lshlrev_b32_e32 v100, 16, v48
	v_mul_f32_e32 v38, 0x4b800000, v41
	v_cmp_gt_f32_e32 vcc, s13, v41
	v_cmp_gt_f32_e64 s[0:1], s13, v40
	v_and_b32_e32 v101, 0xffff0000, v48
	v_cndmask_b32_e32 v38, v41, v38, vcc
	v_mul_f32_e32 v41, 0x4b800000, v40
	v_rsq_f32_e32 v38, v38
	v_cndmask_b32_e64 v40, v40, v41, s[0:1]
	v_rsq_f32_e32 v40, v40
	v_lshlrev_b32_e32 v48, 16, v49
	v_mul_f32_e32 v39, 0x45800000, v38
	v_cndmask_b32_e32 v96, v38, v39, vcc
	v_mul_f32_e32 v38, 0x45800000, v40
	v_cndmask_b32_e64 v98, v40, v38, s[0:1]
	v_pk_mul_f32 v[38:39], v[96:97], v[80:81] op_sel_hi:[0,1]
	v_pk_mul_f32 v[38:39], v[12:13], v[38:39]
	v_pk_mul_f32 v[40:41], v[96:97], v[82:83] op_sel_hi:[0,1]
	v_pk_fma_f32 v[38:39], v[116:117], v[38:39], v[64:65]
	v_pk_mul_f32 v[64:65], v[18:19], 0.5 op_sel_hi:[1,0]
	v_pk_mul_f32 v[40:41], v[14:15], v[40:41]
	v_and_b32_e32 v49, 0xffff0000, v49
	v_pk_fma_f32 v[40:41], v[64:65], v[40:41], v[62:63]
	global_store_dwordx4 v[32:33], v[38:41], off offset:-4096
	v_lshlrev_b32_e32 v102, 16, v44
	v_and_b32_e32 v103, 0xffff0000, v44
	v_pk_mul_f32 v[38:39], v[98:99], v[88:89] op_sel_hi:[0,1]
	v_pk_mul_f32 v[40:41], v[98:99], v[72:73] op_sel_hi:[0,1]
	v_pk_mul_f32 v[38:39], v[12:13], v[38:39]
	v_pk_mul_f32 v[40:41], v[14:15], v[40:41]
	v_pk_fma_f32 v[38:39], v[116:117], v[38:39], v[104:105]
	v_pk_fma_f32 v[40:41], v[64:65], v[40:41], v[46:47]
	global_store_dwordx4 v[32:33], v[38:41], off
	v_pk_mul_f32 v[46:47], v[20:21], 0.5 op_sel_hi:[1,0]
	v_lshlrev_b32_e32 v44, 16, v45
	v_pk_mul_f32 v[38:39], v[96:97], v[84:85] op_sel_hi:[0,1]
	v_pk_mul_f32 v[38:39], v[8:9], v[38:39]
	v_pk_mul_f32 v[40:41], v[96:97], v[86:87] op_sel_hi:[0,1]
	v_pk_fma_f32 v[38:39], v[46:47], v[38:39], v[56:57]
	v_pk_mul_f32 v[56:57], v[22:23], 0.5 op_sel_hi:[1,0]
	v_pk_mul_f32 v[40:41], v[10:11], v[40:41]
	v_and_b32_e32 v45, 0xffff0000, v45
	v_pk_fma_f32 v[40:41], v[56:57], v[40:41], v[50:51]
	global_store_dwordx4 v[32:33], v[38:41], off offset:-3072
	v_add_u32_e32 v148, 2, v148
	v_cmp_ge_i32_e32 vcc, v148, v186
	v_pk_mul_f32 v[38:39], v[98:99], v[90:91] op_sel_hi:[0,1]
	v_pk_mul_f32 v[40:41], v[98:99], v[70:71] op_sel_hi:[0,1]
	v_pk_mul_f32 v[38:39], v[8:9], v[38:39]
	v_pk_mul_f32 v[40:41], v[10:11], v[40:41]
	v_pk_fma_f32 v[38:39], v[46:47], v[38:39], v[106:107]
	v_pk_fma_f32 v[40:41], v[56:57], v[40:41], v[42:43]
	global_store_dwordx4 v[32:33], v[38:41], off offset:1024
	v_pk_mul_f32 v[42:43], v[24:25], 0.5 op_sel_hi:[1,0]
	v_pk_mul_f32 v[46:47], v[26:27], 0.5 op_sel_hi:[1,0]
	v_pk_mul_f32 v[38:39], v[96:97], v[60:61] op_sel_hi:[0,1]
	v_pk_mul_f32 v[40:41], v[96:97], v[58:59] op_sel_hi:[0,1]
	v_pk_mul_f32 v[38:39], v[4:5], v[38:39]
	v_pk_mul_f32 v[40:41], v[6:7], v[40:41]
	v_pk_fma_f32 v[38:39], v[42:43], v[38:39], v[100:101]
	v_pk_fma_f32 v[40:41], v[46:47], v[40:41], v[48:49]
	global_store_dwordx4 v[32:33], v[38:41], off offset:-2048
	s_or_b64 s[6:7], vcc, s[6:7]
	v_lshl_add_u64 v[34:35], v[34:35], 0, s[4:5]
	v_pk_mul_f32 v[38:39], v[98:99], v[92:93] op_sel_hi:[0,1]
	v_pk_mul_f32 v[40:41], v[98:99], v[68:69] op_sel_hi:[0,1]
	v_pk_mul_f32 v[38:39], v[4:5], v[38:39]
	v_pk_mul_f32 v[40:41], v[6:7], v[40:41]
	v_pk_fma_f32 v[38:39], v[42:43], v[38:39], v[108:109]
	v_pk_fma_f32 v[40:41], v[46:47], v[40:41], v[110:111]
	global_store_dwordx4 v[32:33], v[38:41], off offset:2048
	v_pk_mul_f32 v[42:43], v[28:29], 0.5 op_sel_hi:[1,0]
	v_pk_mul_f32 v[46:47], v[30:31], 0.5 op_sel_hi:[1,0]
	v_pk_mul_f32 v[38:39], v[96:97], v[54:55] op_sel_hi:[0,1]
	v_pk_mul_f32 v[40:41], v[96:97], v[52:53] op_sel_hi:[0,1]
	v_pk_mul_f32 v[38:39], v[0:1], v[38:39]
	v_pk_mul_f32 v[40:41], v[2:3], v[40:41]
	v_pk_fma_f32 v[38:39], v[42:43], v[38:39], v[102:103]
	v_pk_fma_f32 v[40:41], v[46:47], v[40:41], v[44:45]
	global_store_dwordx4 v[32:33], v[38:41], off offset:-1024
	s_nop 1
	v_pk_mul_f32 v[38:39], v[98:99], v[94:95] op_sel_hi:[0,1]
	v_pk_mul_f32 v[40:41], v[98:99], v[66:67] op_sel_hi:[0,1]
	v_pk_mul_f32 v[38:39], v[0:1], v[38:39]
	v_pk_mul_f32 v[40:41], v[2:3], v[40:41]
	v_pk_fma_f32 v[38:39], v[42:43], v[38:39], v[112:113]
	v_pk_fma_f32 v[40:41], v[46:47], v[40:41], v[114:115]
	global_store_dwordx4 v[32:33], v[38:41], off offset:3072
	v_lshl_add_u64 v[32:33], v[32:33], 0, s[2:3]
	s_andn2_b64 exec, exec, s[6:7]
	s_cbranch_execz .LBB0_1213
